# batched-x-loads-in-residual-epilogues-with-carry-pad
# baseline (speedup 1.0000x reference)
; __device__ __forceinline__ unsigned cvt_pk_bf16(float lo, float hi) { f32x2_t v = {lo, hi}; bf16x2_t b = __builtin_convertvector(v, bf16x2_t); return __builtin_bit_cast(unsigned, b); }
; __device__ __forceinline__ float bflo(unsigned w) { return __uint_as_float(w << 16); }
; __device__ __forceinline__ float bfhi(unsigned w) { return __uint_as_float(w & 0xffff0000u); }
;     __device__ __forceinline__ void operator()(const f32x4 (&acc)[2][2][4][2], const Unit& u, int wr, int wc, int fr, int fq) const {
;         const int col0 = u.pn * BM + wc * 32 + 8 * fq; const int row0 = u.pm * BM + wr * 64 + fr;
;         const float* gp = gate + (size_t)(u.pm >> 3) * 6144 + col0;
;         f32x4 gv[2][2];
; #pragma unroll
;         for (int bj = 0; bj < 2; ++bj)
; #pragma unroll
;             for (int n = 0; n < 2; ++n) gv[bj][n] = *(const f32x4*)(gp + bj * HALF + n * 4);
; #pragma unroll
;         for (int ai = 0; ai < 2; ++ai)
; #pragma unroll
;             for (int m = 0; m < 4; ++m) { const size_t off = (size_t)(row0 + ai * HALF + m * 16) * 1024 + col0;
; #pragma unroll
;                 for (int bj = 0; bj < 2; ++bj) {
;                     f32x4 x0, x1;
;                     if (xin_f32) { x0 = *(const f32x4*)(xin_f32 + off + bj * HALF); x1 = *(const f32x4*)(xin_f32 + off + bj * HALF + 4); }
;                     else { const u32x4 w = *(const u32x4*)(xin_b + off + bj * HALF); x0 = (f32x4){bflo(w.x), bfhi(w.x), bflo(w.y), bfhi(w.y)}; x1 = (f32x4){bflo(w.z), bfhi(w.z), bflo(w.w), bfhi(w.w)}; }
;                     x0 = x0 + gv[bj][0] * acc[ai][bj][m][0]; x1 = x1 + gv[bj][1] * acc[ai][bj][m][1];
;                     if (xout_f32) { *(f32x4*)(xout_f32 + off + bj * HALF) = x0; *(f32x4*)(xout_f32 + off + bj * HALF + 4) = x1; }
;                     else { u32x4 w; w.x = cvt_pk_bf16(x0[0], x0[1]); w.y = cvt_pk_bf16(x0[2], x0[3]); w.z = cvt_pk_bf16(x1[0], x1[1]); w.w = cvt_pk_bf16(x1[2], x1[3]); *(u32x4*)(xout_b + off + bj * HALF) = w; }
.LBB0_975:
	v_mov_b32_e32 v146, v206
	s_lshl_b32 s1, s43, 8
	v_readfirstlane_b32 s0, v146
	s_lshr_b32 s22, s0, 1
	s_and_b32 s22, s22, 0x60
	s_or_b32 s1, s22, s1
	v_lshrrev_b32_e32 v0, 1, v146
	s_ashr_i32 s0, s0, 2
	v_and_or_b32 v0, v0, 24, s1
	s_lshl_b32 s1, s42, 8
	s_andn2_b32 s0, s0, 63
	s_add_i32 s22, s0, s1
	s_ashr_i32 s0, s42, 3
	s_mul_hi_i32 s1, s0, 0x6000
	s_mulk_i32 s0, 0x6000
	s_add_u32 s0, s35, s0
	s_addc_u32 s1, s36, s1
	v_lshl_add_u64 v[74:75], v[0:1], 2, s[0:1]
	global_load_dwordx4 v[94:97], v[74:75], off
	global_load_dwordx4 v[90:93], v[74:75], off offset:16
	global_load_dwordx4 v[78:81], v[74:75], off offset:512
	s_nop 0
	global_load_dwordx4 v[74:77], v[74:75], off offset:528
	v_and_or_b32 v174, v146, 15, s22
	v_ashrrev_i32_e32 v175, 31, v174
	v_lshlrev_b64 v[176:177], 10, v[174:175]
	v_or_b32_e32 v176, v176, v0
	v_cndmask_b32_e64 v146, 0, 1, s[16:17]
	v_cmp_ne_u32_e64 s[0:1], 1, v146
	s_andn2_b64 vcc, exec, s[16:17]
	v_lshl_add_u64 v[178:179], v[176:177], 2, s[12:13]
	v_lshl_add_u64 v[208:209], v[176:177], 1, s[2:3]
	v_mov_b32_e32 v210, v178
	v_mov_b32_e32 v211, v179
	s_cmp_lg_u64 s[16:17], 0
	s_cbranch_scc1 .Lmix_epi_f32
	global_load_dwordx4 v[146:149], v[208:209], off
	global_load_dwordx4 v[150:153], v[208:209], off offset:256
	v_add_co_u32_e32 v250, vcc, 0x8000, v208
	s_nop 1
	v_addc_co_u32_e32 v251, vcc, 0, v209, vcc
	global_load_dwordx4 v[154:157], v[250:251], off
	global_load_dwordx4 v[158:161], v[250:251], off offset:256
	v_add_co_u32_e32 v250, vcc, 0x10000, v208
	s_nop 1
	v_addc_co_u32_e32 v251, vcc, 0, v209, vcc
	global_load_dwordx4 v[162:165], v[250:251], off
	global_load_dwordx4 v[182:185], v[250:251], off offset:256
	v_add_co_u32_e32 v250, vcc, 0x18000, v208
	s_nop 1
	v_addc_co_u32_e32 v251, vcc, 0, v209, vcc
	global_load_dwordx4 v[186:189], v[250:251], off
	global_load_dwordx4 v[190:193], v[250:251], off offset:256
	v_add_co_u32_e32 v250, vcc, 0x40000, v208
	s_nop 1
	v_addc_co_u32_e32 v251, vcc, 0, v209, vcc
	global_load_dwordx4 v[194:197], v[250:251], off
	global_load_dwordx4 v[198:201], v[250:251], off offset:256
	v_add_co_u32_e32 v250, vcc, 0x48000, v208
	s_nop 1
	v_addc_co_u32_e32 v251, vcc, 0, v209, vcc
	global_load_dwordx4 v[202:205], v[250:251], off
	global_load_dwordx4 v[218:221], v[250:251], off offset:256
	v_add_co_u32_e32 v250, vcc, 0x50000, v208
	s_nop 1
	v_addc_co_u32_e32 v251, vcc, 0, v209, vcc
	global_load_dwordx4 v[222:225], v[250:251], off
	global_load_dwordx4 v[242:245], v[250:251], off offset:256
	v_add_co_u32_e32 v250, vcc, 0x58000, v208
	s_nop 1
	v_addc_co_u32_e32 v251, vcc, 0, v209, vcc
	global_load_dwordx4 v[246:249], v[250:251], off
	global_load_dwordx4 v[174:177], v[250:251], off offset:256
	s_waitcnt vmcnt(0)
	v_and_b32_e32 v212, 0xffff0000, v146
	v_lshlrev_b32_e32 v146, 16, v146
	v_fma_f32 v142, v142, v94, v146
	v_fma_f32 v143, v143, v95, v212
	v_and_b32_e32 v212, 0xffff0000, v147
	v_lshlrev_b32_e32 v147, 16, v147
	v_fma_f32 v144, v144, v96, v147
	v_fma_f32 v145, v145, v97, v212
	v_and_b32_e32 v212, 0xffff0000, v148
	v_lshlrev_b32_e32 v148, 16, v148
	v_fma_f32 v138, v138, v90, v148
	v_fma_f32 v139, v139, v91, v212
	v_and_b32_e32 v212, 0xffff0000, v149
	v_lshlrev_b32_e32 v149, 16, v149
	v_fma_f32 v140, v140, v92, v149
	v_fma_f32 v141, v141, v93, v212
	v_cvt_pk_bf16_f32 v142, v142, v143
	v_cvt_pk_bf16_f32 v143, v144, v145
	v_cvt_pk_bf16_f32 v144, v138, v139
	v_cvt_pk_bf16_f32 v145, v140, v141
	v_and_b32_e32 v212, 0xffff0000, v150
	v_lshlrev_b32_e32 v150, 16, v150
	v_fma_f32 v134, v134, v78, v150
	v_fma_f32 v135, v135, v79, v212
	v_and_b32_e32 v212, 0xffff0000, v151
	v_lshlrev_b32_e32 v151, 16, v151
	v_fma_f32 v136, v136, v80, v151
	v_fma_f32 v137, v137, v81, v212
	v_and_b32_e32 v212, 0xffff0000, v152
	v_lshlrev_b32_e32 v152, 16, v152
	v_fma_f32 v130, v130, v74, v152
	v_fma_f32 v131, v131, v75, v212
	v_and_b32_e32 v212, 0xffff0000, v153
	v_lshlrev_b32_e32 v153, 16, v153
	v_fma_f32 v132, v132, v76, v153
	v_fma_f32 v133, v133, v77, v212
	v_cvt_pk_bf16_f32 v134, v134, v135
	v_cvt_pk_bf16_f32 v135, v136, v137
	v_cvt_pk_bf16_f32 v136, v130, v131
	v_cvt_pk_bf16_f32 v137, v132, v133
	global_store_dwordx4 v[208:209], v[142:145], off
	global_store_dwordx4 v[208:209], v[134:137], off offset:256
	v_and_b32_e32 v212, 0xffff0000, v154
	v_lshlrev_b32_e32 v154, 16, v154
	v_fma_f32 v126, v126, v94, v154
	v_fma_f32 v127, v127, v95, v212
	v_and_b32_e32 v212, 0xffff0000, v155
	v_lshlrev_b32_e32 v155, 16, v155
	v_fma_f32 v128, v128, v96, v155
	v_fma_f32 v129, v129, v97, v212
	v_and_b32_e32 v212, 0xffff0000, v156
	v_lshlrev_b32_e32 v156, 16, v156
	v_fma_f32 v122, v122, v90, v156
	v_fma_f32 v123, v123, v91, v212
	v_and_b32_e32 v212, 0xffff0000, v157
	v_lshlrev_b32_e32 v157, 16, v157
	v_fma_f32 v124, v124, v92, v157
	v_fma_f32 v125, v125, v93, v212
	v_cvt_pk_bf16_f32 v126, v126, v127
	v_cvt_pk_bf16_f32 v127, v128, v129
	v_cvt_pk_bf16_f32 v128, v122, v123
	v_cvt_pk_bf16_f32 v129, v124, v125
	v_and_b32_e32 v212, 0xffff0000, v158
	v_lshlrev_b32_e32 v158, 16, v158
	v_fma_f32 v118, v118, v78, v158
	v_fma_f32 v119, v119, v79, v212
	v_and_b32_e32 v212, 0xffff0000, v159
	v_lshlrev_b32_e32 v159, 16, v159
	v_fma_f32 v120, v120, v80, v159
	v_fma_f32 v121, v121, v81, v212
	v_and_b32_e32 v212, 0xffff0000, v160
	v_lshlrev_b32_e32 v160, 16, v160
	v_fma_f32 v114, v114, v74, v160
	v_fma_f32 v115, v115, v75, v212
	v_and_b32_e32 v212, 0xffff0000, v161
	v_lshlrev_b32_e32 v161, 16, v161
	v_fma_f32 v116, v116, v76, v161
	v_fma_f32 v117, v117, v77, v212
	v_cvt_pk_bf16_f32 v118, v118, v119
	v_cvt_pk_bf16_f32 v119, v120, v121
	v_cvt_pk_bf16_f32 v120, v114, v115
	v_cvt_pk_bf16_f32 v121, v116, v117
	v_add_co_u32_e32 v250, vcc, 0x8000, v208
; __device__ __forceinline__ unsigned cvt_pk_bf16(float lo, float hi) { f32x2_t v = {lo, hi}; bf16x2_t b = __builtin_convertvector(v, bf16x2_t); return __builtin_bit_cast(unsigned, b); }
; __device__ __forceinline__ float bflo(unsigned w) { return __uint_as_float(w << 16); }
; __device__ __forceinline__ float bfhi(unsigned w) { return __uint_as_float(w & 0xffff0000u); }
;     __device__ __forceinline__ void operator()(const f32x4 (&acc)[2][2][4][2], const Unit& u, int wr, int wc, int fr, int fq) const {
;     ...
;             for (int m = 0; m < 4; ++m) { const size_t off = (size_t)(row0 + ai * HALF + m * 16) * 1024 + col0;
; #pragma unroll
;                 for (int bj = 0; bj < 2; ++bj) {
;                     f32x4 x0, x1;
;                     if (xin_f32) { x0 = *(const f32x4*)(xin_f32 + off + bj * HALF); x1 = *(const f32x4*)(xin_f32 + off + bj * HALF + 4); }
;                     else { const u32x4 w = *(const u32x4*)(xin_b + off + bj * HALF); x0 = (f32x4){bflo(w.x), bfhi(w.x), bflo(w.y), bfhi(w.y)}; x1 = (f32x4){bflo(w.z), bfhi(w.z), bflo(w.w), bfhi(w.w)}; }
;                     x0 = x0 + gv[bj][0] * acc[ai][bj][m][0]; x1 = x1 + gv[bj][1] * acc[ai][bj][m][1];
;                     if (xout_f32) { *(f32x4*)(xout_f32 + off + bj * HALF) = x0; *(f32x4*)(xout_f32 + off + bj * HALF + 4) = x1; }
;                     else { u32x4 w; w.x = cvt_pk_bf16(x0[0], x0[1]); w.y = cvt_pk_bf16(x0[2], x0[3]); w.z = cvt_pk_bf16(x1[0], x1[1]); w.w = cvt_pk_bf16(x1[2], x1[3]); *(u32x4*)(xout_b + off + bj * HALF) = w; }
	s_nop 1
	v_addc_co_u32_e32 v251, vcc, 0, v209, vcc
	global_store_dwordx4 v[250:251], v[126:129], off
	global_store_dwordx4 v[250:251], v[118:121], off offset:256
	v_and_b32_e32 v212, 0xffff0000, v162
	v_lshlrev_b32_e32 v162, 16, v162
	v_fma_f32 v110, v110, v94, v162
	v_fma_f32 v111, v111, v95, v212
	v_and_b32_e32 v212, 0xffff0000, v163
	v_lshlrev_b32_e32 v163, 16, v163
	v_fma_f32 v112, v112, v96, v163
	v_fma_f32 v113, v113, v97, v212
	v_and_b32_e32 v212, 0xffff0000, v164
	v_lshlrev_b32_e32 v164, 16, v164
	v_fma_f32 v106, v106, v90, v164
	v_fma_f32 v107, v107, v91, v212
	v_and_b32_e32 v212, 0xffff0000, v165
	v_lshlrev_b32_e32 v165, 16, v165
	v_fma_f32 v108, v108, v92, v165
	v_fma_f32 v109, v109, v93, v212
	v_cvt_pk_bf16_f32 v110, v110, v111
	v_cvt_pk_bf16_f32 v111, v112, v113
	v_cvt_pk_bf16_f32 v112, v106, v107
	v_cvt_pk_bf16_f32 v113, v108, v109
	v_and_b32_e32 v212, 0xffff0000, v182
	v_lshlrev_b32_e32 v182, 16, v182
	v_fma_f32 v102, v102, v78, v182
	v_fma_f32 v103, v103, v79, v212
	v_and_b32_e32 v212, 0xffff0000, v183
	v_lshlrev_b32_e32 v183, 16, v183
	v_fma_f32 v104, v104, v80, v183
	v_fma_f32 v105, v105, v81, v212
	v_and_b32_e32 v212, 0xffff0000, v184
	v_lshlrev_b32_e32 v184, 16, v184
	v_fma_f32 v98, v98, v74, v184
	v_fma_f32 v99, v99, v75, v212
	v_and_b32_e32 v212, 0xffff0000, v185
	v_lshlrev_b32_e32 v185, 16, v185
	v_fma_f32 v100, v100, v76, v185
	v_fma_f32 v101, v101, v77, v212
	v_cvt_pk_bf16_f32 v102, v102, v103
	v_cvt_pk_bf16_f32 v103, v104, v105
	v_cvt_pk_bf16_f32 v104, v98, v99
	v_cvt_pk_bf16_f32 v105, v100, v101
	v_add_co_u32_e32 v250, vcc, 0x10000, v208
	s_nop 1
	v_addc_co_u32_e32 v251, vcc, 0, v209, vcc
	global_store_dwordx4 v[250:251], v[110:113], off
	global_store_dwordx4 v[250:251], v[102:105], off offset:256
	v_and_b32_e32 v212, 0xffff0000, v186
	v_lshlrev_b32_e32 v186, 16, v186
	v_fma_f32 v86, v86, v94, v186
	v_fma_f32 v87, v87, v95, v212
	v_and_b32_e32 v212, 0xffff0000, v187
	v_lshlrev_b32_e32 v187, 16, v187
	v_fma_f32 v88, v88, v96, v187
	v_fma_f32 v89, v89, v97, v212
	v_and_b32_e32 v212, 0xffff0000, v188
	v_lshlrev_b32_e32 v188, 16, v188
	v_fma_f32 v82, v82, v90, v188
	v_fma_f32 v83, v83, v91, v212
	v_and_b32_e32 v212, 0xffff0000, v189
	v_lshlrev_b32_e32 v189, 16, v189
	v_fma_f32 v84, v84, v92, v189
	v_fma_f32 v85, v85, v93, v212
	v_cvt_pk_bf16_f32 v86, v86, v87
	v_cvt_pk_bf16_f32 v87, v88, v89
	v_cvt_pk_bf16_f32 v88, v82, v83
	v_cvt_pk_bf16_f32 v89, v84, v85
	v_and_b32_e32 v212, 0xffff0000, v190
	v_lshlrev_b32_e32 v190, 16, v190
	v_fma_f32 v70, v70, v78, v190
	v_fma_f32 v71, v71, v79, v212
	v_and_b32_e32 v212, 0xffff0000, v191
	v_lshlrev_b32_e32 v191, 16, v191
	v_fma_f32 v72, v72, v80, v191
	v_fma_f32 v73, v73, v81, v212
	v_and_b32_e32 v212, 0xffff0000, v192
	v_lshlrev_b32_e32 v192, 16, v192
	v_fma_f32 v66, v66, v74, v192
	v_fma_f32 v67, v67, v75, v212
	v_and_b32_e32 v212, 0xffff0000, v193
	v_lshlrev_b32_e32 v193, 16, v193
	v_fma_f32 v68, v68, v76, v193
	v_fma_f32 v69, v69, v77, v212
	v_cvt_pk_bf16_f32 v70, v70, v71
	v_cvt_pk_bf16_f32 v71, v72, v73
	v_cvt_pk_bf16_f32 v72, v66, v67
	v_cvt_pk_bf16_f32 v73, v68, v69
	v_add_co_u32_e32 v250, vcc, 0x18000, v208
	s_nop 1
	v_addc_co_u32_e32 v251, vcc, 0, v209, vcc
	global_store_dwordx4 v[250:251], v[86:89], off
	global_store_dwordx4 v[250:251], v[70:73], off offset:256
	v_and_b32_e32 v212, 0xffff0000, v194
	v_lshlrev_b32_e32 v194, 16, v194
	v_fma_f32 v62, v62, v94, v194
	v_fma_f32 v63, v63, v95, v212
	v_and_b32_e32 v212, 0xffff0000, v195
	v_lshlrev_b32_e32 v195, 16, v195
	v_fma_f32 v64, v64, v96, v195
	v_fma_f32 v65, v65, v97, v212
	v_and_b32_e32 v212, 0xffff0000, v196
	v_lshlrev_b32_e32 v196, 16, v196
	v_fma_f32 v58, v58, v90, v196
	v_fma_f32 v59, v59, v91, v212
	v_and_b32_e32 v212, 0xffff0000, v197
	v_lshlrev_b32_e32 v197, 16, v197
	v_fma_f32 v60, v60, v92, v197
	v_fma_f32 v61, v61, v93, v212
	v_cvt_pk_bf16_f32 v62, v62, v63
	v_cvt_pk_bf16_f32 v63, v64, v65
	v_cvt_pk_bf16_f32 v64, v58, v59
	v_cvt_pk_bf16_f32 v65, v60, v61
	v_and_b32_e32 v212, 0xffff0000, v198
	v_lshlrev_b32_e32 v198, 16, v198
	v_fma_f32 v54, v54, v78, v198
	v_fma_f32 v55, v55, v79, v212
	v_and_b32_e32 v212, 0xffff0000, v199
	v_lshlrev_b32_e32 v199, 16, v199
	v_fma_f32 v56, v56, v80, v199
	v_fma_f32 v57, v57, v81, v212
	v_and_b32_e32 v212, 0xffff0000, v200
	v_lshlrev_b32_e32 v200, 16, v200
	v_fma_f32 v50, v50, v74, v200
	v_fma_f32 v51, v51, v75, v212
	v_and_b32_e32 v212, 0xffff0000, v201
	v_lshlrev_b32_e32 v201, 16, v201
	v_fma_f32 v52, v52, v76, v201
	v_fma_f32 v53, v53, v77, v212
	v_cvt_pk_bf16_f32 v54, v54, v55
	v_cvt_pk_bf16_f32 v55, v56, v57
	v_cvt_pk_bf16_f32 v56, v50, v51
	v_cvt_pk_bf16_f32 v57, v52, v53
	v_add_co_u32_e32 v250, vcc, 0x40000, v208
	s_nop 1
	v_addc_co_u32_e32 v251, vcc, 0, v209, vcc
	global_store_dwordx4 v[250:251], v[62:65], off
	global_store_dwordx4 v[250:251], v[54:57], off offset:256
	v_and_b32_e32 v212, 0xffff0000, v202
	v_lshlrev_b32_e32 v202, 16, v202
	v_fma_f32 v46, v46, v94, v202
	v_fma_f32 v47, v47, v95, v212
	v_and_b32_e32 v212, 0xffff0000, v203
	v_lshlrev_b32_e32 v203, 16, v203
	v_fma_f32 v48, v48, v96, v203
	v_fma_f32 v49, v49, v97, v212
	v_and_b32_e32 v212, 0xffff0000, v204
	v_lshlrev_b32_e32 v204, 16, v204
	v_fma_f32 v42, v42, v90, v204
	v_fma_f32 v43, v43, v91, v212
	v_and_b32_e32 v212, 0xffff0000, v205
	v_lshlrev_b32_e32 v205, 16, v205
	v_fma_f32 v44, v44, v92, v205
	v_fma_f32 v45, v45, v93, v212
	v_cvt_pk_bf16_f32 v46, v46, v47
	v_cvt_pk_bf16_f32 v47, v48, v49
	v_cvt_pk_bf16_f32 v48, v42, v43
	v_cvt_pk_bf16_f32 v49, v44, v45
	v_and_b32_e32 v212, 0xffff0000, v218
	v_lshlrev_b32_e32 v218, 16, v218
	v_fma_f32 v38, v38, v78, v218
	v_fma_f32 v39, v39, v79, v212
; __device__ __forceinline__ unsigned cvt_pk_bf16(float lo, float hi) { f32x2_t v = {lo, hi}; bf16x2_t b = __builtin_convertvector(v, bf16x2_t); return __builtin_bit_cast(unsigned, b); }
; __device__ __forceinline__ float bflo(unsigned w) { return __uint_as_float(w << 16); }
; __device__ __forceinline__ float bfhi(unsigned w) { return __uint_as_float(w & 0xffff0000u); }
;     __device__ __forceinline__ void operator()(const f32x4 (&acc)[2][2][4][2], const Unit& u, int wr, int wc, int fr, int fq) const {
;     ...
;             for (int m = 0; m < 4; ++m) { const size_t off = (size_t)(row0 + ai * HALF + m * 16) * 1024 + col0;
; #pragma unroll
;                 for (int bj = 0; bj < 2; ++bj) {
;                     f32x4 x0, x1;
;                     if (xin_f32) { x0 = *(const f32x4*)(xin_f32 + off + bj * HALF); x1 = *(const f32x4*)(xin_f32 + off + bj * HALF + 4); }
;                     else { const u32x4 w = *(const u32x4*)(xin_b + off + bj * HALF); x0 = (f32x4){bflo(w.x), bfhi(w.x), bflo(w.y), bfhi(w.y)}; x1 = (f32x4){bflo(w.z), bfhi(w.z), bflo(w.w), bfhi(w.w)}; }
;                     x0 = x0 + gv[bj][0] * acc[ai][bj][m][0]; x1 = x1 + gv[bj][1] * acc[ai][bj][m][1];
;                     if (xout_f32) { *(f32x4*)(xout_f32 + off + bj * HALF) = x0; *(f32x4*)(xout_f32 + off + bj * HALF + 4) = x1; }
;                     else { u32x4 w; w.x = cvt_pk_bf16(x0[0], x0[1]); w.y = cvt_pk_bf16(x0[2], x0[3]); w.z = cvt_pk_bf16(x1[0], x1[1]); w.w = cvt_pk_bf16(x1[2], x1[3]); *(u32x4*)(xout_b + off + bj * HALF) = w; }
	v_and_b32_e32 v212, 0xffff0000, v219
	v_lshlrev_b32_e32 v219, 16, v219
	v_fma_f32 v40, v40, v80, v219
	v_fma_f32 v41, v41, v81, v212
	v_and_b32_e32 v212, 0xffff0000, v220
	v_lshlrev_b32_e32 v220, 16, v220
	v_fma_f32 v34, v34, v74, v220
	v_fma_f32 v35, v35, v75, v212
	v_and_b32_e32 v212, 0xffff0000, v221
	v_lshlrev_b32_e32 v221, 16, v221
	v_fma_f32 v36, v36, v76, v221
	v_fma_f32 v37, v37, v77, v212
	v_cvt_pk_bf16_f32 v38, v38, v39
	v_cvt_pk_bf16_f32 v39, v40, v41
	v_cvt_pk_bf16_f32 v40, v34, v35
	v_cvt_pk_bf16_f32 v41, v36, v37
	v_add_co_u32_e32 v250, vcc, 0x48000, v208
	s_nop 1
	v_addc_co_u32_e32 v251, vcc, 0, v209, vcc
	global_store_dwordx4 v[250:251], v[46:49], off
	global_store_dwordx4 v[250:251], v[38:41], off offset:256
	v_and_b32_e32 v212, 0xffff0000, v222
	v_lshlrev_b32_e32 v222, 16, v222
	v_fma_f32 v30, v30, v94, v222
	v_fma_f32 v31, v31, v95, v212
	v_and_b32_e32 v212, 0xffff0000, v223
	v_lshlrev_b32_e32 v223, 16, v223
	v_fma_f32 v32, v32, v96, v223
	v_fma_f32 v33, v33, v97, v212
	v_and_b32_e32 v212, 0xffff0000, v224
	v_lshlrev_b32_e32 v224, 16, v224
	v_fma_f32 v26, v26, v90, v224
	v_fma_f32 v27, v27, v91, v212
	v_and_b32_e32 v212, 0xffff0000, v225
	v_lshlrev_b32_e32 v225, 16, v225
	v_fma_f32 v28, v28, v92, v225
	v_fma_f32 v29, v29, v93, v212
	v_cvt_pk_bf16_f32 v30, v30, v31
	v_cvt_pk_bf16_f32 v31, v32, v33
	v_cvt_pk_bf16_f32 v32, v26, v27
	v_cvt_pk_bf16_f32 v33, v28, v29
	v_and_b32_e32 v212, 0xffff0000, v242
	v_lshlrev_b32_e32 v242, 16, v242
	v_fma_f32 v22, v22, v78, v242
	v_fma_f32 v23, v23, v79, v212
	v_and_b32_e32 v212, 0xffff0000, v243
	v_lshlrev_b32_e32 v243, 16, v243
	v_fma_f32 v24, v24, v80, v243
	v_fma_f32 v25, v25, v81, v212
	v_and_b32_e32 v212, 0xffff0000, v244
	v_lshlrev_b32_e32 v244, 16, v244
	v_fma_f32 v18, v18, v74, v244
	v_fma_f32 v19, v19, v75, v212
	v_and_b32_e32 v212, 0xffff0000, v245
	v_lshlrev_b32_e32 v245, 16, v245
	v_fma_f32 v20, v20, v76, v245
	v_fma_f32 v21, v21, v77, v212
	v_cvt_pk_bf16_f32 v22, v22, v23
	v_cvt_pk_bf16_f32 v23, v24, v25
	v_cvt_pk_bf16_f32 v24, v18, v19
	v_cvt_pk_bf16_f32 v25, v20, v21
	v_add_co_u32_e32 v250, vcc, 0x50000, v208
	s_nop 1
	v_addc_co_u32_e32 v251, vcc, 0, v209, vcc
	global_store_dwordx4 v[250:251], v[30:33], off
	global_store_dwordx4 v[250:251], v[22:25], off offset:256
	v_and_b32_e32 v212, 0xffff0000, v246
	v_lshlrev_b32_e32 v246, 16, v246
	v_fma_f32 v14, v14, v94, v246
	v_fma_f32 v15, v15, v95, v212
	v_and_b32_e32 v212, 0xffff0000, v247
	v_lshlrev_b32_e32 v247, 16, v247
	v_fma_f32 v16, v16, v96, v247
	v_fma_f32 v17, v17, v97, v212
	v_and_b32_e32 v212, 0xffff0000, v248
	v_lshlrev_b32_e32 v248, 16, v248
	v_fma_f32 v10, v10, v90, v248
	v_fma_f32 v11, v11, v91, v212
	v_and_b32_e32 v212, 0xffff0000, v249
	v_lshlrev_b32_e32 v249, 16, v249
	v_fma_f32 v12, v12, v92, v249
	v_fma_f32 v13, v13, v93, v212
	v_cvt_pk_bf16_f32 v14, v14, v15
	v_cvt_pk_bf16_f32 v15, v16, v17
	v_cvt_pk_bf16_f32 v16, v10, v11
	v_cvt_pk_bf16_f32 v17, v12, v13
	v_and_b32_e32 v212, 0xffff0000, v174
	v_lshlrev_b32_e32 v174, 16, v174
	v_fma_f32 v6, v6, v78, v174
	v_fma_f32 v7, v7, v79, v212
	v_and_b32_e32 v212, 0xffff0000, v175
	v_lshlrev_b32_e32 v175, 16, v175
	v_fma_f32 v8, v8, v80, v175
	v_fma_f32 v9, v9, v81, v212
	v_and_b32_e32 v212, 0xffff0000, v176
	v_lshlrev_b32_e32 v176, 16, v176
	v_fma_f32 v2, v2, v74, v176
	v_fma_f32 v3, v3, v75, v212
	v_and_b32_e32 v212, 0xffff0000, v177
	v_lshlrev_b32_e32 v177, 16, v177
	v_fma_f32 v4, v4, v76, v177
	v_fma_f32 v5, v5, v77, v212
	v_cvt_pk_bf16_f32 v6, v6, v7
	v_cvt_pk_bf16_f32 v7, v8, v9
	v_cvt_pk_bf16_f32 v8, v2, v3
	v_cvt_pk_bf16_f32 v9, v4, v5
	v_add_co_u32_e32 v250, vcc, 0x58000, v208
	s_nop 1
	v_addc_co_u32_e32 v251, vcc, 0, v209, vcc
	global_store_dwordx4 v[250:251], v[14:17], off
	global_store_dwordx4 v[250:251], v[6:9], off offset:256
	s_branch .Lmix_epi_done
.Lmix_epi_f32:
	global_load_dwordx4 v[146:149], v[210:211], off
	global_load_dwordx4 v[150:153], v[210:211], off offset:16
	global_load_dwordx4 v[154:157], v[210:211], off offset:512
	global_load_dwordx4 v[158:161], v[210:211], off offset:528
	v_add_co_u32_e32 v250, vcc, 0x10000, v210
	s_nop 1
	v_addc_co_u32_e32 v251, vcc, 0, v211, vcc
	global_load_dwordx4 v[162:165], v[250:251], off
	global_load_dwordx4 v[182:185], v[250:251], off offset:16
	global_load_dwordx4 v[186:189], v[250:251], off offset:512
	global_load_dwordx4 v[190:193], v[250:251], off offset:528
	v_add_co_u32_e32 v250, vcc, 0x20000, v210
	s_nop 1
	v_addc_co_u32_e32 v251, vcc, 0, v211, vcc
	global_load_dwordx4 v[194:197], v[250:251], off
	global_load_dwordx4 v[198:201], v[250:251], off offset:16
	global_load_dwordx4 v[202:205], v[250:251], off offset:512
	global_load_dwordx4 v[218:221], v[250:251], off offset:528
	v_add_co_u32_e32 v250, vcc, 0x30000, v210
	s_nop 1
	v_addc_co_u32_e32 v251, vcc, 0, v211, vcc
	global_load_dwordx4 v[222:225], v[250:251], off
	global_load_dwordx4 v[242:245], v[250:251], off offset:16
	global_load_dwordx4 v[246:249], v[250:251], off offset:512
	global_load_dwordx4 v[174:177], v[250:251], off offset:528
	s_waitcnt vmcnt(0)
; __device__ __forceinline__ unsigned cvt_pk_bf16(float lo, float hi) { f32x2_t v = {lo, hi}; bf16x2_t b = __builtin_convertvector(v, bf16x2_t); return __builtin_bit_cast(unsigned, b); }
; __device__ __forceinline__ float bflo(unsigned w) { return __uint_as_float(w << 16); }
; __device__ __forceinline__ float bfhi(unsigned w) { return __uint_as_float(w & 0xffff0000u); }
;     __device__ __forceinline__ void operator()(const f32x4 (&acc)[2][2][4][2], const Unit& u, int wr, int wc, int fr, int fq) const {
;     ...
;             for (int m = 0; m < 4; ++m) { const size_t off = (size_t)(row0 + ai * HALF + m * 16) * 1024 + col0;
; #pragma unroll
;                 for (int bj = 0; bj < 2; ++bj) {
;                     f32x4 x0, x1;
;                     if (xin_f32) { x0 = *(const f32x4*)(xin_f32 + off + bj * HALF); x1 = *(const f32x4*)(xin_f32 + off + bj * HALF + 4); }
;                     else { const u32x4 w = *(const u32x4*)(xin_b + off + bj * HALF); x0 = (f32x4){bflo(w.x), bfhi(w.x), bflo(w.y), bfhi(w.y)}; x1 = (f32x4){bflo(w.z), bfhi(w.z), bflo(w.w), bfhi(w.w)}; }
;                     x0 = x0 + gv[bj][0] * acc[ai][bj][m][0]; x1 = x1 + gv[bj][1] * acc[ai][bj][m][1];
;                     if (xout_f32) { *(f32x4*)(xout_f32 + off + bj * HALF) = x0; *(f32x4*)(xout_f32 + off + bj * HALF + 4) = x1; }
;                     else { u32x4 w; w.x = cvt_pk_bf16(x0[0], x0[1]); w.y = cvt_pk_bf16(x0[2], x0[3]); w.z = cvt_pk_bf16(x1[0], x1[1]); w.w = cvt_pk_bf16(x1[2], x1[3]); *(u32x4*)(xout_b + off + bj * HALF) = w; }
	v_fma_f32 v142, v142, v94, v146
	v_fma_f32 v143, v143, v95, v147
	v_fma_f32 v144, v144, v96, v148
	v_fma_f32 v145, v145, v97, v149
	v_fma_f32 v138, v138, v90, v150
	v_fma_f32 v139, v139, v91, v151
	v_fma_f32 v140, v140, v92, v152
	v_fma_f32 v141, v141, v93, v153
	v_cvt_pk_bf16_f32 v142, v142, v143
	v_cvt_pk_bf16_f32 v143, v144, v145
	v_cvt_pk_bf16_f32 v144, v138, v139
	v_cvt_pk_bf16_f32 v145, v140, v141
	v_fma_f32 v134, v134, v78, v154
	v_fma_f32 v135, v135, v79, v155
	v_fma_f32 v136, v136, v80, v156
	v_fma_f32 v137, v137, v81, v157
	v_fma_f32 v130, v130, v74, v158
	v_fma_f32 v131, v131, v75, v159
	v_fma_f32 v132, v132, v76, v160
	v_fma_f32 v133, v133, v77, v161
	v_cvt_pk_bf16_f32 v134, v134, v135
	v_cvt_pk_bf16_f32 v135, v136, v137
	v_cvt_pk_bf16_f32 v136, v130, v131
	v_cvt_pk_bf16_f32 v137, v132, v133
	global_store_dwordx4 v[208:209], v[142:145], off
	global_store_dwordx4 v[208:209], v[134:137], off offset:256
	v_fma_f32 v126, v126, v94, v162
	v_fma_f32 v127, v127, v95, v163
	v_fma_f32 v128, v128, v96, v164
	v_fma_f32 v129, v129, v97, v165
	v_fma_f32 v122, v122, v90, v182
	v_fma_f32 v123, v123, v91, v183
	v_fma_f32 v124, v124, v92, v184
	v_fma_f32 v125, v125, v93, v185
	v_cvt_pk_bf16_f32 v126, v126, v127
	v_cvt_pk_bf16_f32 v127, v128, v129
	v_cvt_pk_bf16_f32 v128, v122, v123
	v_cvt_pk_bf16_f32 v129, v124, v125
	v_fma_f32 v118, v118, v78, v186
	v_fma_f32 v119, v119, v79, v187
	v_fma_f32 v120, v120, v80, v188
	v_fma_f32 v121, v121, v81, v189
	v_fma_f32 v114, v114, v74, v190
	v_fma_f32 v115, v115, v75, v191
	v_fma_f32 v116, v116, v76, v192
	v_fma_f32 v117, v117, v77, v193
	v_cvt_pk_bf16_f32 v118, v118, v119
	v_cvt_pk_bf16_f32 v119, v120, v121
	v_cvt_pk_bf16_f32 v120, v114, v115
	v_cvt_pk_bf16_f32 v121, v116, v117
	v_add_co_u32_e32 v250, vcc, 0x8000, v208
	s_nop 1
	v_addc_co_u32_e32 v251, vcc, 0, v209, vcc
	global_store_dwordx4 v[250:251], v[126:129], off
	global_store_dwordx4 v[250:251], v[118:121], off offset:256
	v_fma_f32 v110, v110, v94, v194
	v_fma_f32 v111, v111, v95, v195
	v_fma_f32 v112, v112, v96, v196
	v_fma_f32 v113, v113, v97, v197
	v_fma_f32 v106, v106, v90, v198
	v_fma_f32 v107, v107, v91, v199
	v_fma_f32 v108, v108, v92, v200
	v_fma_f32 v109, v109, v93, v201
	v_cvt_pk_bf16_f32 v110, v110, v111
	v_cvt_pk_bf16_f32 v111, v112, v113
	v_cvt_pk_bf16_f32 v112, v106, v107
	v_cvt_pk_bf16_f32 v113, v108, v109
	v_fma_f32 v102, v102, v78, v202
	v_fma_f32 v103, v103, v79, v203
	v_fma_f32 v104, v104, v80, v204
	v_fma_f32 v105, v105, v81, v205
	v_fma_f32 v98, v98, v74, v218
	v_fma_f32 v99, v99, v75, v219
	v_fma_f32 v100, v100, v76, v220
	v_fma_f32 v101, v101, v77, v221
	v_cvt_pk_bf16_f32 v102, v102, v103
	v_cvt_pk_bf16_f32 v103, v104, v105
	v_cvt_pk_bf16_f32 v104, v98, v99
	v_cvt_pk_bf16_f32 v105, v100, v101
	v_add_co_u32_e32 v250, vcc, 0x10000, v208
	s_nop 1
	v_addc_co_u32_e32 v251, vcc, 0, v209, vcc
	global_store_dwordx4 v[250:251], v[110:113], off
	global_store_dwordx4 v[250:251], v[102:105], off offset:256
	v_fma_f32 v86, v86, v94, v222
	v_fma_f32 v87, v87, v95, v223
	v_fma_f32 v88, v88, v96, v224
	v_fma_f32 v89, v89, v97, v225
	v_fma_f32 v82, v82, v90, v242
	v_fma_f32 v83, v83, v91, v243
	v_fma_f32 v84, v84, v92, v244
	v_fma_f32 v85, v85, v93, v245
	v_cvt_pk_bf16_f32 v86, v86, v87
	v_cvt_pk_bf16_f32 v87, v88, v89
	v_cvt_pk_bf16_f32 v88, v82, v83
	v_cvt_pk_bf16_f32 v89, v84, v85
	v_fma_f32 v70, v70, v78, v246
	v_fma_f32 v71, v71, v79, v247
	v_fma_f32 v72, v72, v80, v248
	v_fma_f32 v73, v73, v81, v249
	v_fma_f32 v66, v66, v74, v174
	v_fma_f32 v67, v67, v75, v175
	v_fma_f32 v68, v68, v76, v176
	v_fma_f32 v69, v69, v77, v177
	v_cvt_pk_bf16_f32 v70, v70, v71
	v_cvt_pk_bf16_f32 v71, v72, v73
	v_cvt_pk_bf16_f32 v72, v66, v67
	v_cvt_pk_bf16_f32 v73, v68, v69
	v_add_co_u32_e32 v250, vcc, 0x18000, v208
	s_nop 1
	v_addc_co_u32_e32 v251, vcc, 0, v209, vcc
	global_store_dwordx4 v[250:251], v[86:89], off
	global_store_dwordx4 v[250:251], v[70:73], off offset:256
	v_add_co_u32_e32 v250, vcc, 0x80000, v210
	s_nop 1
	v_addc_co_u32_e32 v251, vcc, 0, v211, vcc
	global_load_dwordx4 v[146:149], v[250:251], off
	global_load_dwordx4 v[150:153], v[250:251], off offset:16
	global_load_dwordx4 v[154:157], v[250:251], off offset:512
	global_load_dwordx4 v[158:161], v[250:251], off offset:528
	v_add_co_u32_e32 v250, vcc, 0x90000, v210
	s_nop 1
	v_addc_co_u32_e32 v251, vcc, 0, v211, vcc
	global_load_dwordx4 v[162:165], v[250:251], off
	global_load_dwordx4 v[182:185], v[250:251], off offset:16
	global_load_dwordx4 v[186:189], v[250:251], off offset:512
	global_load_dwordx4 v[190:193], v[250:251], off offset:528
	v_add_co_u32_e32 v250, vcc, 0xa0000, v210
	s_nop 1
	v_addc_co_u32_e32 v251, vcc, 0, v211, vcc
	global_load_dwordx4 v[194:197], v[250:251], off
	global_load_dwordx4 v[198:201], v[250:251], off offset:16
	global_load_dwordx4 v[202:205], v[250:251], off offset:512
	global_load_dwordx4 v[218:221], v[250:251], off offset:528
	v_add_co_u32_e32 v250, vcc, 0xb0000, v210
	s_nop 1
	v_addc_co_u32_e32 v251, vcc, 0, v211, vcc
	global_load_dwordx4 v[222:225], v[250:251], off
	global_load_dwordx4 v[242:245], v[250:251], off offset:16
	global_load_dwordx4 v[246:249], v[250:251], off offset:512
	global_load_dwordx4 v[174:177], v[250:251], off offset:528
	s_waitcnt vmcnt(0)
; __device__ __forceinline__ unsigned cvt_pk_bf16(float lo, float hi) { f32x2_t v = {lo, hi}; bf16x2_t b = __builtin_convertvector(v, bf16x2_t); return __builtin_bit_cast(unsigned, b); }
; __device__ __forceinline__ float bflo(unsigned w) { return __uint_as_float(w << 16); }
; __device__ __forceinline__ float bfhi(unsigned w) { return __uint_as_float(w & 0xffff0000u); }
;     __device__ __forceinline__ void operator()(const f32x4 (&acc)[2][2][4][2], const Unit& u, int wr, int wc, int fr, int fq) const {
;     ...
;             for (int m = 0; m < 4; ++m) { const size_t off = (size_t)(row0 + ai * HALF + m * 16) * 1024 + col0;
; #pragma unroll
;                 for (int bj = 0; bj < 2; ++bj) {
;                     f32x4 x0, x1;
;                     if (xin_f32) { x0 = *(const f32x4*)(xin_f32 + off + bj * HALF); x1 = *(const f32x4*)(xin_f32 + off + bj * HALF + 4); }
;                     else { const u32x4 w = *(const u32x4*)(xin_b + off + bj * HALF); x0 = (f32x4){bflo(w.x), bfhi(w.x), bflo(w.y), bfhi(w.y)}; x1 = (f32x4){bflo(w.z), bfhi(w.z), bflo(w.w), bfhi(w.w)}; }
;                     x0 = x0 + gv[bj][0] * acc[ai][bj][m][0]; x1 = x1 + gv[bj][1] * acc[ai][bj][m][1];
;                     if (xout_f32) { *(f32x4*)(xout_f32 + off + bj * HALF) = x0; *(f32x4*)(xout_f32 + off + bj * HALF + 4) = x1; }
;                     else { u32x4 w; w.x = cvt_pk_bf16(x0[0], x0[1]); w.y = cvt_pk_bf16(x0[2], x0[3]); w.z = cvt_pk_bf16(x1[0], x1[1]); w.w = cvt_pk_bf16(x1[2], x1[3]); *(u32x4*)(xout_b + off + bj * HALF) = w; }
	v_fma_f32 v62, v62, v94, v146
	v_fma_f32 v63, v63, v95, v147
	v_fma_f32 v64, v64, v96, v148
	v_fma_f32 v65, v65, v97, v149
	v_fma_f32 v58, v58, v90, v150
	v_fma_f32 v59, v59, v91, v151
	v_fma_f32 v60, v60, v92, v152
	v_fma_f32 v61, v61, v93, v153
	v_cvt_pk_bf16_f32 v62, v62, v63
	v_cvt_pk_bf16_f32 v63, v64, v65
	v_cvt_pk_bf16_f32 v64, v58, v59
	v_cvt_pk_bf16_f32 v65, v60, v61
	v_fma_f32 v54, v54, v78, v154
	v_fma_f32 v55, v55, v79, v155
	v_fma_f32 v56, v56, v80, v156
	v_fma_f32 v57, v57, v81, v157
	v_fma_f32 v50, v50, v74, v158
	v_fma_f32 v51, v51, v75, v159
	v_fma_f32 v52, v52, v76, v160
	v_fma_f32 v53, v53, v77, v161
	v_cvt_pk_bf16_f32 v54, v54, v55
	v_cvt_pk_bf16_f32 v55, v56, v57
	v_cvt_pk_bf16_f32 v56, v50, v51
	v_cvt_pk_bf16_f32 v57, v52, v53
	v_add_co_u32_e32 v250, vcc, 0x40000, v208
	s_nop 1
	v_addc_co_u32_e32 v251, vcc, 0, v209, vcc
	global_store_dwordx4 v[250:251], v[62:65], off
	global_store_dwordx4 v[250:251], v[54:57], off offset:256
	v_fma_f32 v46, v46, v94, v162
	v_fma_f32 v47, v47, v95, v163
	v_fma_f32 v48, v48, v96, v164
	v_fma_f32 v49, v49, v97, v165
	v_fma_f32 v42, v42, v90, v182
	v_fma_f32 v43, v43, v91, v183
	v_fma_f32 v44, v44, v92, v184
	v_fma_f32 v45, v45, v93, v185
	v_cvt_pk_bf16_f32 v46, v46, v47
	v_cvt_pk_bf16_f32 v47, v48, v49
	v_cvt_pk_bf16_f32 v48, v42, v43
	v_cvt_pk_bf16_f32 v49, v44, v45
	v_fma_f32 v38, v38, v78, v186
	v_fma_f32 v39, v39, v79, v187
	v_fma_f32 v40, v40, v80, v188
	v_fma_f32 v41, v41, v81, v189
	v_fma_f32 v34, v34, v74, v190
	v_fma_f32 v35, v35, v75, v191
	v_fma_f32 v36, v36, v76, v192
	v_fma_f32 v37, v37, v77, v193
	v_cvt_pk_bf16_f32 v38, v38, v39
	v_cvt_pk_bf16_f32 v39, v40, v41
	v_cvt_pk_bf16_f32 v40, v34, v35
	v_cvt_pk_bf16_f32 v41, v36, v37
	v_add_co_u32_e32 v250, vcc, 0x48000, v208
	s_nop 1
	v_addc_co_u32_e32 v251, vcc, 0, v209, vcc
	global_store_dwordx4 v[250:251], v[46:49], off
	global_store_dwordx4 v[250:251], v[38:41], off offset:256
	v_fma_f32 v30, v30, v94, v194
	v_fma_f32 v31, v31, v95, v195
	v_fma_f32 v32, v32, v96, v196
	v_fma_f32 v33, v33, v97, v197
	v_fma_f32 v26, v26, v90, v198
	v_fma_f32 v27, v27, v91, v199
	v_fma_f32 v28, v28, v92, v200
	v_fma_f32 v29, v29, v93, v201
	v_cvt_pk_bf16_f32 v30, v30, v31
	v_cvt_pk_bf16_f32 v31, v32, v33
	v_cvt_pk_bf16_f32 v32, v26, v27
	v_cvt_pk_bf16_f32 v33, v28, v29
	v_fma_f32 v22, v22, v78, v202
	v_fma_f32 v23, v23, v79, v203
	v_fma_f32 v24, v24, v80, v204
	v_fma_f32 v25, v25, v81, v205
	v_fma_f32 v18, v18, v74, v218
	v_fma_f32 v19, v19, v75, v219
	v_fma_f32 v20, v20, v76, v220
	v_fma_f32 v21, v21, v77, v221
	v_cvt_pk_bf16_f32 v22, v22, v23
	v_cvt_pk_bf16_f32 v23, v24, v25
	v_cvt_pk_bf16_f32 v24, v18, v19
	v_cvt_pk_bf16_f32 v25, v20, v21
	v_add_co_u32_e32 v250, vcc, 0x50000, v208
	s_nop 1
	v_addc_co_u32_e32 v251, vcc, 0, v209, vcc
	global_store_dwordx4 v[250:251], v[30:33], off
	global_store_dwordx4 v[250:251], v[22:25], off offset:256
	v_fma_f32 v14, v14, v94, v222
	v_fma_f32 v15, v15, v95, v223
	v_fma_f32 v16, v16, v96, v224
	v_fma_f32 v17, v17, v97, v225
	v_fma_f32 v10, v10, v90, v242
	v_fma_f32 v11, v11, v91, v243
	v_fma_f32 v12, v12, v92, v244
	v_fma_f32 v13, v13, v93, v245
	v_cvt_pk_bf16_f32 v14, v14, v15
	v_cvt_pk_bf16_f32 v15, v16, v17
	v_cvt_pk_bf16_f32 v16, v10, v11
	v_cvt_pk_bf16_f32 v17, v12, v13
	v_fma_f32 v6, v6, v78, v246
	v_fma_f32 v7, v7, v79, v247
	v_fma_f32 v8, v8, v80, v248
	v_fma_f32 v9, v9, v81, v249
	v_fma_f32 v2, v2, v74, v174
	v_fma_f32 v3, v3, v75, v175
	v_fma_f32 v4, v4, v76, v176
	v_fma_f32 v5, v5, v77, v177
	v_cvt_pk_bf16_f32 v6, v6, v7
	v_cvt_pk_bf16_f32 v7, v8, v9
	v_cvt_pk_bf16_f32 v8, v2, v3
	v_cvt_pk_bf16_f32 v9, v4, v5
	v_add_co_u32_e32 v250, vcc, 0x58000, v208
	s_nop 1
	v_addc_co_u32_e32 v251, vcc, 0, v209, vcc
	global_store_dwordx4 v[250:251], v[14:17], off
	global_store_dwordx4 v[250:251], v[6:9], off offset:256

; __device__ __forceinline__ unsigned cvt_pk_bf16(float lo, float hi) { f32x2_t v = {lo, hi}; bf16x2_t b = __builtin_convertvector(v, bf16x2_t); return __builtin_bit_cast(unsigned, b); }
; __device__ __forceinline__ float bflo(unsigned w) { return __uint_as_float(w << 16); }
; __device__ __forceinline__ float bfhi(unsigned w) { return __uint_as_float(w & 0xffff0000u); }
;     __device__ __forceinline__ void operator()(const f32x4 (&acc)[2][2][4][2], const Unit& u, int wr, int wc, int fr, int fq) const {
;         const int col0 = u.pn * BM + wc * 32 + 8 * fq; const int row0 = u.pm * BM + wr * 64 + fr;
;         const float* gp = gate + (size_t)(u.pm >> 3) * 6144 + col0;
;         f32x4 gv[2][2];
; #pragma unroll
;         for (int bj = 0; bj < 2; ++bj)
; #pragma unroll
;             for (int n = 0; n < 2; ++n) gv[bj][n] = *(const f32x4*)(gp + bj * HALF + n * 4);
; #pragma unroll
;         for (int ai = 0; ai < 2; ++ai)
; #pragma unroll
;             for (int m = 0; m < 4; ++m) { const size_t off = (size_t)(row0 + ai * HALF + m * 16) * 1024 + col0;
; #pragma unroll
;                 for (int bj = 0; bj < 2; ++bj) {
;                     f32x4 x0, x1;
;                     if (xin_f32) { x0 = *(const f32x4*)(xin_f32 + off + bj * HALF); x1 = *(const f32x4*)(xin_f32 + off + bj * HALF + 4); }
;                     else { const u32x4 w = *(const u32x4*)(xin_b + off + bj * HALF); x0 = (f32x4){bflo(w.x), bfhi(w.x), bflo(w.y), bfhi(w.y)}; x1 = (f32x4){bflo(w.z), bfhi(w.z), bflo(w.w), bfhi(w.w)}; }
;                     x0 = x0 + gv[bj][0] * acc[ai][bj][m][0]; x1 = x1 + gv[bj][1] * acc[ai][bj][m][1];
;                     if (xout_f32) { *(f32x4*)(xout_f32 + off + bj * HALF) = x0; *(f32x4*)(xout_f32 + off + bj * HALF + 4) = x1; }
;                     else { u32x4 w; w.x = cvt_pk_bf16(x0[0], x0[1]); w.y = cvt_pk_bf16(x0[2], x0[3]); w.z = cvt_pk_bf16(x1[0], x1[1]); w.w = cvt_pk_bf16(x1[2], x1[3]); *(u32x4*)(xout_b + off + bj * HALF) = w; }
.LBB0_1183:
	v_mov_b32_e32 v82, v206
	s_lshl_b32 s19, s26, 8
	v_readfirstlane_b32 s5, v82
	s_lshr_b32 s21, s5, 1
	s_and_b32 s21, s21, 0x60
	s_or_b32 s19, s21, s19
	v_lshrrev_b32_e32 v83, 1, v82
	s_ashr_i32 s5, s5, 2
	v_and_or_b32 v152, v83, 24, s19
	s_lshl_b32 s19, s4, 8
	s_andn2_b32 s5, s5, 63
	s_add_i32 s5, s5, s19
	v_and_or_b32 v166, v82, 15, s5
	v_ashrrev_i32_e32 v167, 31, v166
	v_ashrrev_i32_e32 v153, 31, v152
	v_lshlrev_b64 v[82:83], 10, v[166:167]
	v_lshl_add_u64 v[158:159], v[82:83], 0, v[152:153]
	s_ashr_i32 s4, s4, 3
	v_lshl_add_u64 v[168:169], v[158:159], 1, s[2:3]
	s_mul_hi_i32 s5, s4, 0x6000
	s_mulk_i32 s4, 0x6000
	s_add_u32 s4, s46, s4
	s_addc_u32 s5, s47, s5
	v_lshl_add_u64 v[82:83], v[152:153], 2, s[4:5]
	global_load_dwordx4 v[102:105], v[82:83], off
	global_load_dwordx4 v[98:101], v[82:83], off offset:16
	global_load_dwordx4 v[86:89], v[82:83], off offset:512
	s_nop 0
	global_load_dwordx4 v[82:85], v[82:83], off offset:528
	v_cndmask_b32_e64 v160, 0, 1, s[16:17]
	v_cmp_ne_u32_e64 s[4:5], 1, v160
	s_andn2_b64 vcc, exec, s[16:17]
	v_lshl_add_u64 v[170:171], v[158:159], 2, s[12:13]
	v_mov_b32_e32 v208, v168
	v_mov_b32_e32 v209, v169
	v_mov_b32_e32 v210, v170
	v_mov_b32_e32 v211, v171
	global_load_dwordx4 v[152:155], v[208:209], off
	global_load_dwordx4 v[156:159], v[208:209], off offset:256
	v_add_co_u32_e32 v250, vcc, 0x8000, v208
	s_nop 1
	v_addc_co_u32_e32 v251, vcc, 0, v209, vcc
	global_load_dwordx4 v[160:163], v[250:251], off
	global_load_dwordx4 v[164:167], v[250:251], off offset:256
	v_add_co_u32_e32 v250, vcc, 0x10000, v208
	s_nop 1
	v_addc_co_u32_e32 v251, vcc, 0, v209, vcc
	global_load_dwordx4 v[168:171], v[250:251], off
	global_load_dwordx4 v[174:177], v[250:251], off offset:256
	v_add_co_u32_e32 v250, vcc, 0x18000, v208
	s_nop 1
	v_addc_co_u32_e32 v251, vcc, 0, v209, vcc
	global_load_dwordx4 v[178:181], v[250:251], off
	global_load_dwordx4 v[182:185], v[250:251], off offset:256
	v_add_co_u32_e32 v250, vcc, 0x40000, v208
	s_nop 1
	v_addc_co_u32_e32 v251, vcc, 0, v209, vcc
	global_load_dwordx4 v[186:189], v[250:251], off
	global_load_dwordx4 v[190:193], v[250:251], off offset:256
	v_add_co_u32_e32 v250, vcc, 0x48000, v208
	s_nop 1
	v_addc_co_u32_e32 v251, vcc, 0, v209, vcc
	global_load_dwordx4 v[194:197], v[250:251], off
	global_load_dwordx4 v[198:201], v[250:251], off offset:256
	v_add_co_u32_e32 v250, vcc, 0x50000, v208
	s_nop 1
	v_addc_co_u32_e32 v251, vcc, 0, v209, vcc
	global_load_dwordx4 v[218:221], v[250:251], off
	global_load_dwordx4 v[222:225], v[250:251], off offset:256
	v_add_co_u32_e32 v250, vcc, 0x58000, v208
	s_nop 1
	v_addc_co_u32_e32 v251, vcc, 0, v209, vcc
	global_load_dwordx4 v[242:245], v[250:251], off
	global_load_dwordx4 v[246:249], v[250:251], off offset:256
	s_cmp_lg_u64 s[16:17], 0
	s_waitcnt vmcnt(0)
	s_cbranch_scc1 .Ldown_epi_f32
	v_and_b32_e32 v212, 0xffff0000, v152
	v_lshlrev_b32_e32 v152, 16, v152
	v_fma_f32 v142, v142, v102, v152
	v_fma_f32 v143, v143, v103, v212
	v_and_b32_e32 v212, 0xffff0000, v153
	v_lshlrev_b32_e32 v153, 16, v153
	v_fma_f32 v144, v144, v104, v153
	v_fma_f32 v145, v145, v105, v212
	v_and_b32_e32 v212, 0xffff0000, v154
	v_lshlrev_b32_e32 v154, 16, v154
	v_fma_f32 v138, v138, v98, v154
	v_fma_f32 v139, v139, v99, v212
	v_and_b32_e32 v212, 0xffff0000, v155
	v_lshlrev_b32_e32 v155, 16, v155
	v_fma_f32 v140, v140, v100, v155
	v_fma_f32 v141, v141, v101, v212
	v_cvt_pk_bf16_f32 v142, v142, v143
	v_cvt_pk_bf16_f32 v143, v144, v145
	v_cvt_pk_bf16_f32 v144, v138, v139
	v_cvt_pk_bf16_f32 v145, v140, v141
	v_and_b32_e32 v212, 0xffff0000, v156
	v_lshlrev_b32_e32 v156, 16, v156
	v_fma_f32 v134, v134, v86, v156
	v_fma_f32 v135, v135, v87, v212
	v_and_b32_e32 v212, 0xffff0000, v157
	v_lshlrev_b32_e32 v157, 16, v157
	v_fma_f32 v136, v136, v88, v157
	v_fma_f32 v137, v137, v89, v212
	v_and_b32_e32 v212, 0xffff0000, v158
	v_lshlrev_b32_e32 v158, 16, v158
	v_fma_f32 v130, v130, v82, v158
	v_fma_f32 v131, v131, v83, v212
	v_and_b32_e32 v212, 0xffff0000, v159
	v_lshlrev_b32_e32 v159, 16, v159
	v_fma_f32 v132, v132, v84, v159
	v_fma_f32 v133, v133, v85, v212
	v_cvt_pk_bf16_f32 v134, v134, v135
	v_cvt_pk_bf16_f32 v135, v136, v137
	v_cvt_pk_bf16_f32 v136, v130, v131
	v_cvt_pk_bf16_f32 v137, v132, v133
	global_store_dwordx4 v[208:209], v[142:145], off
	global_store_dwordx4 v[208:209], v[134:137], off offset:256
	v_and_b32_e32 v212, 0xffff0000, v160
	v_lshlrev_b32_e32 v160, 16, v160
	v_fma_f32 v126, v126, v102, v160
	v_fma_f32 v127, v127, v103, v212
	v_and_b32_e32 v212, 0xffff0000, v161
	v_lshlrev_b32_e32 v161, 16, v161
	v_fma_f32 v128, v128, v104, v161
	v_fma_f32 v129, v129, v105, v212
	v_and_b32_e32 v212, 0xffff0000, v162
	v_lshlrev_b32_e32 v162, 16, v162
	v_fma_f32 v122, v122, v98, v162
	v_fma_f32 v123, v123, v99, v212
	v_and_b32_e32 v212, 0xffff0000, v163
	v_lshlrev_b32_e32 v163, 16, v163
	v_fma_f32 v124, v124, v100, v163
	v_fma_f32 v125, v125, v101, v212
	v_cvt_pk_bf16_f32 v126, v126, v127
	v_cvt_pk_bf16_f32 v127, v128, v129
	v_cvt_pk_bf16_f32 v128, v122, v123
	v_cvt_pk_bf16_f32 v129, v124, v125
	v_and_b32_e32 v212, 0xffff0000, v164
	v_lshlrev_b32_e32 v164, 16, v164
	v_fma_f32 v118, v118, v86, v164
	v_fma_f32 v119, v119, v87, v212
	v_and_b32_e32 v212, 0xffff0000, v165
	v_lshlrev_b32_e32 v165, 16, v165
	v_fma_f32 v120, v120, v88, v165
	v_fma_f32 v121, v121, v89, v212
	v_and_b32_e32 v212, 0xffff0000, v166
	v_lshlrev_b32_e32 v166, 16, v166
	v_fma_f32 v114, v114, v82, v166
	v_fma_f32 v115, v115, v83, v212
	v_and_b32_e32 v212, 0xffff0000, v167
	v_lshlrev_b32_e32 v167, 16, v167
	v_fma_f32 v116, v116, v84, v167
	v_fma_f32 v117, v117, v85, v212
	v_cvt_pk_bf16_f32 v118, v118, v119
; __device__ __forceinline__ unsigned cvt_pk_bf16(float lo, float hi) { f32x2_t v = {lo, hi}; bf16x2_t b = __builtin_convertvector(v, bf16x2_t); return __builtin_bit_cast(unsigned, b); }
; __device__ __forceinline__ float bflo(unsigned w) { return __uint_as_float(w << 16); }
; __device__ __forceinline__ float bfhi(unsigned w) { return __uint_as_float(w & 0xffff0000u); }
;     __device__ __forceinline__ void operator()(const f32x4 (&acc)[2][2][4][2], const Unit& u, int wr, int wc, int fr, int fq) const {
;     ...
;             for (int m = 0; m < 4; ++m) { const size_t off = (size_t)(row0 + ai * HALF + m * 16) * 1024 + col0;
; #pragma unroll
;                 for (int bj = 0; bj < 2; ++bj) {
;                     f32x4 x0, x1;
;                     if (xin_f32) { x0 = *(const f32x4*)(xin_f32 + off + bj * HALF); x1 = *(const f32x4*)(xin_f32 + off + bj * HALF + 4); }
;                     else { const u32x4 w = *(const u32x4*)(xin_b + off + bj * HALF); x0 = (f32x4){bflo(w.x), bfhi(w.x), bflo(w.y), bfhi(w.y)}; x1 = (f32x4){bflo(w.z), bfhi(w.z), bflo(w.w), bfhi(w.w)}; }
;                     x0 = x0 + gv[bj][0] * acc[ai][bj][m][0]; x1 = x1 + gv[bj][1] * acc[ai][bj][m][1];
;                     if (xout_f32) { *(f32x4*)(xout_f32 + off + bj * HALF) = x0; *(f32x4*)(xout_f32 + off + bj * HALF + 4) = x1; }
;                     else { u32x4 w; w.x = cvt_pk_bf16(x0[0], x0[1]); w.y = cvt_pk_bf16(x0[2], x0[3]); w.z = cvt_pk_bf16(x1[0], x1[1]); w.w = cvt_pk_bf16(x1[2], x1[3]); *(u32x4*)(xout_b + off + bj * HALF) = w; }
	v_cvt_pk_bf16_f32 v119, v120, v121
	v_cvt_pk_bf16_f32 v120, v114, v115
	v_cvt_pk_bf16_f32 v121, v116, v117
	v_add_co_u32_e32 v250, vcc, 0x8000, v208
	s_nop 1
	v_addc_co_u32_e32 v251, vcc, 0, v209, vcc
	global_store_dwordx4 v[250:251], v[126:129], off
	global_store_dwordx4 v[250:251], v[118:121], off offset:256
	v_and_b32_e32 v212, 0xffff0000, v168
	v_lshlrev_b32_e32 v168, 16, v168
	v_fma_f32 v110, v110, v102, v168
	v_fma_f32 v111, v111, v103, v212
	v_and_b32_e32 v212, 0xffff0000, v169
	v_lshlrev_b32_e32 v169, 16, v169
	v_fma_f32 v112, v112, v104, v169
	v_fma_f32 v113, v113, v105, v212
	v_and_b32_e32 v212, 0xffff0000, v170
	v_lshlrev_b32_e32 v170, 16, v170
	v_fma_f32 v106, v106, v98, v170
	v_fma_f32 v107, v107, v99, v212
	v_and_b32_e32 v212, 0xffff0000, v171
	v_lshlrev_b32_e32 v171, 16, v171
	v_fma_f32 v108, v108, v100, v171
	v_fma_f32 v109, v109, v101, v212
	v_cvt_pk_bf16_f32 v110, v110, v111
	v_cvt_pk_bf16_f32 v111, v112, v113
	v_cvt_pk_bf16_f32 v112, v106, v107
	v_cvt_pk_bf16_f32 v113, v108, v109
	v_and_b32_e32 v212, 0xffff0000, v174
	v_lshlrev_b32_e32 v174, 16, v174
	v_fma_f32 v94, v94, v86, v174
	v_fma_f32 v95, v95, v87, v212
	v_and_b32_e32 v212, 0xffff0000, v175
	v_lshlrev_b32_e32 v175, 16, v175
	v_fma_f32 v96, v96, v88, v175
	v_fma_f32 v97, v97, v89, v212
	v_and_b32_e32 v212, 0xffff0000, v176
	v_lshlrev_b32_e32 v176, 16, v176
	v_fma_f32 v90, v90, v82, v176
	v_fma_f32 v91, v91, v83, v212
	v_and_b32_e32 v212, 0xffff0000, v177
	v_lshlrev_b32_e32 v177, 16, v177
	v_fma_f32 v92, v92, v84, v177
	v_fma_f32 v93, v93, v85, v212
	v_cvt_pk_bf16_f32 v94, v94, v95
	v_cvt_pk_bf16_f32 v95, v96, v97
	v_cvt_pk_bf16_f32 v96, v90, v91
	v_cvt_pk_bf16_f32 v97, v92, v93
	v_add_co_u32_e32 v250, vcc, 0x10000, v208
	s_nop 1
	v_addc_co_u32_e32 v251, vcc, 0, v209, vcc
	global_store_dwordx4 v[250:251], v[110:113], off
	global_store_dwordx4 v[250:251], v[94:97], off offset:256
	v_and_b32_e32 v212, 0xffff0000, v178
	v_lshlrev_b32_e32 v178, 16, v178
	v_fma_f32 v78, v78, v102, v178
	v_fma_f32 v79, v79, v103, v212
	v_and_b32_e32 v212, 0xffff0000, v179
	v_lshlrev_b32_e32 v179, 16, v179
	v_fma_f32 v80, v80, v104, v179
	v_fma_f32 v81, v81, v105, v212
	v_and_b32_e32 v212, 0xffff0000, v180
	v_lshlrev_b32_e32 v180, 16, v180
	v_fma_f32 v74, v74, v98, v180
	v_fma_f32 v75, v75, v99, v212
	v_and_b32_e32 v212, 0xffff0000, v181
	v_lshlrev_b32_e32 v181, 16, v181
	v_fma_f32 v76, v76, v100, v181
	v_fma_f32 v77, v77, v101, v212
	v_cvt_pk_bf16_f32 v78, v78, v79
	v_cvt_pk_bf16_f32 v79, v80, v81
	v_cvt_pk_bf16_f32 v80, v74, v75
	v_cvt_pk_bf16_f32 v81, v76, v77
	v_and_b32_e32 v212, 0xffff0000, v182
	v_lshlrev_b32_e32 v182, 16, v182
	v_fma_f32 v70, v70, v86, v182
	v_fma_f32 v71, v71, v87, v212
	v_and_b32_e32 v212, 0xffff0000, v183
	v_lshlrev_b32_e32 v183, 16, v183
	v_fma_f32 v72, v72, v88, v183
	v_fma_f32 v73, v73, v89, v212
	v_and_b32_e32 v212, 0xffff0000, v184
	v_lshlrev_b32_e32 v184, 16, v184
	v_fma_f32 v66, v66, v82, v184
	v_fma_f32 v67, v67, v83, v212
	v_and_b32_e32 v212, 0xffff0000, v185
	v_lshlrev_b32_e32 v185, 16, v185
	v_fma_f32 v68, v68, v84, v185
	v_fma_f32 v69, v69, v85, v212
	v_cvt_pk_bf16_f32 v70, v70, v71
	v_cvt_pk_bf16_f32 v71, v72, v73
	v_cvt_pk_bf16_f32 v72, v66, v67
	v_cvt_pk_bf16_f32 v73, v68, v69
	v_add_co_u32_e32 v250, vcc, 0x18000, v208
	s_nop 1
	v_addc_co_u32_e32 v251, vcc, 0, v209, vcc
	global_store_dwordx4 v[250:251], v[78:81], off
	global_store_dwordx4 v[250:251], v[70:73], off offset:256
	v_and_b32_e32 v212, 0xffff0000, v186
	v_lshlrev_b32_e32 v186, 16, v186
	v_fma_f32 v62, v62, v102, v186
	v_fma_f32 v63, v63, v103, v212
	v_and_b32_e32 v212, 0xffff0000, v187
	v_lshlrev_b32_e32 v187, 16, v187
	v_fma_f32 v64, v64, v104, v187
	v_fma_f32 v65, v65, v105, v212
	v_and_b32_e32 v212, 0xffff0000, v188
	v_lshlrev_b32_e32 v188, 16, v188
	v_fma_f32 v58, v58, v98, v188
	v_fma_f32 v59, v59, v99, v212
	v_and_b32_e32 v212, 0xffff0000, v189
	v_lshlrev_b32_e32 v189, 16, v189
	v_fma_f32 v60, v60, v100, v189
	v_fma_f32 v61, v61, v101, v212
	v_cvt_pk_bf16_f32 v62, v62, v63
	v_cvt_pk_bf16_f32 v63, v64, v65
	v_cvt_pk_bf16_f32 v64, v58, v59
	v_cvt_pk_bf16_f32 v65, v60, v61
	v_and_b32_e32 v212, 0xffff0000, v190
	v_lshlrev_b32_e32 v190, 16, v190
	v_fma_f32 v54, v54, v86, v190
	v_fma_f32 v55, v55, v87, v212
	v_and_b32_e32 v212, 0xffff0000, v191
	v_lshlrev_b32_e32 v191, 16, v191
	v_fma_f32 v56, v56, v88, v191
	v_fma_f32 v57, v57, v89, v212
	v_and_b32_e32 v212, 0xffff0000, v192
	v_lshlrev_b32_e32 v192, 16, v192
	v_fma_f32 v50, v50, v82, v192
	v_fma_f32 v51, v51, v83, v212
	v_and_b32_e32 v212, 0xffff0000, v193
	v_lshlrev_b32_e32 v193, 16, v193
	v_fma_f32 v52, v52, v84, v193
	v_fma_f32 v53, v53, v85, v212
	v_cvt_pk_bf16_f32 v54, v54, v55
	v_cvt_pk_bf16_f32 v55, v56, v57
	v_cvt_pk_bf16_f32 v56, v50, v51
	v_cvt_pk_bf16_f32 v57, v52, v53
	v_add_co_u32_e32 v250, vcc, 0x40000, v208
	s_nop 1
	v_addc_co_u32_e32 v251, vcc, 0, v209, vcc
	global_store_dwordx4 v[250:251], v[62:65], off
	global_store_dwordx4 v[250:251], v[54:57], off offset:256
	v_and_b32_e32 v212, 0xffff0000, v194
	v_lshlrev_b32_e32 v194, 16, v194
	v_fma_f32 v46, v46, v102, v194
	v_fma_f32 v47, v47, v103, v212
	v_and_b32_e32 v212, 0xffff0000, v195
	v_lshlrev_b32_e32 v195, 16, v195
	v_fma_f32 v48, v48, v104, v195
	v_fma_f32 v49, v49, v105, v212
	v_and_b32_e32 v212, 0xffff0000, v196
	v_lshlrev_b32_e32 v196, 16, v196
	v_fma_f32 v42, v42, v98, v196
	v_fma_f32 v43, v43, v99, v212
	v_and_b32_e32 v212, 0xffff0000, v197
	v_lshlrev_b32_e32 v197, 16, v197
	v_fma_f32 v44, v44, v100, v197
	v_fma_f32 v45, v45, v101, v212
	v_cvt_pk_bf16_f32 v46, v46, v47
	v_cvt_pk_bf16_f32 v47, v48, v49
	v_cvt_pk_bf16_f32 v48, v42, v43
	v_cvt_pk_bf16_f32 v49, v44, v45
; __device__ __forceinline__ unsigned cvt_pk_bf16(float lo, float hi) { f32x2_t v = {lo, hi}; bf16x2_t b = __builtin_convertvector(v, bf16x2_t); return __builtin_bit_cast(unsigned, b); }
; __device__ __forceinline__ float bflo(unsigned w) { return __uint_as_float(w << 16); }
; __device__ __forceinline__ float bfhi(unsigned w) { return __uint_as_float(w & 0xffff0000u); }
;     __device__ __forceinline__ void operator()(const f32x4 (&acc)[2][2][4][2], const Unit& u, int wr, int wc, int fr, int fq) const {
;     ...
;             for (int m = 0; m < 4; ++m) { const size_t off = (size_t)(row0 + ai * HALF + m * 16) * 1024 + col0;
; #pragma unroll
;                 for (int bj = 0; bj < 2; ++bj) {
;                     f32x4 x0, x1;
;                     if (xin_f32) { x0 = *(const f32x4*)(xin_f32 + off + bj * HALF); x1 = *(const f32x4*)(xin_f32 + off + bj * HALF + 4); }
;                     else { const u32x4 w = *(const u32x4*)(xin_b + off + bj * HALF); x0 = (f32x4){bflo(w.x), bfhi(w.x), bflo(w.y), bfhi(w.y)}; x1 = (f32x4){bflo(w.z), bfhi(w.z), bflo(w.w), bfhi(w.w)}; }
;                     x0 = x0 + gv[bj][0] * acc[ai][bj][m][0]; x1 = x1 + gv[bj][1] * acc[ai][bj][m][1];
;                     if (xout_f32) { *(f32x4*)(xout_f32 + off + bj * HALF) = x0; *(f32x4*)(xout_f32 + off + bj * HALF + 4) = x1; }
;                     else { u32x4 w; w.x = cvt_pk_bf16(x0[0], x0[1]); w.y = cvt_pk_bf16(x0[2], x0[3]); w.z = cvt_pk_bf16(x1[0], x1[1]); w.w = cvt_pk_bf16(x1[2], x1[3]); *(u32x4*)(xout_b + off + bj * HALF) = w; }
	v_and_b32_e32 v212, 0xffff0000, v198
	v_lshlrev_b32_e32 v198, 16, v198
	v_fma_f32 v38, v38, v86, v198
	v_fma_f32 v39, v39, v87, v212
	v_and_b32_e32 v212, 0xffff0000, v199
	v_lshlrev_b32_e32 v199, 16, v199
	v_fma_f32 v40, v40, v88, v199
	v_fma_f32 v41, v41, v89, v212
	v_and_b32_e32 v212, 0xffff0000, v200
	v_lshlrev_b32_e32 v200, 16, v200
	v_fma_f32 v34, v34, v82, v200
	v_fma_f32 v35, v35, v83, v212
	v_and_b32_e32 v212, 0xffff0000, v201
	v_lshlrev_b32_e32 v201, 16, v201
	v_fma_f32 v36, v36, v84, v201
	v_fma_f32 v37, v37, v85, v212
	v_cvt_pk_bf16_f32 v38, v38, v39
	v_cvt_pk_bf16_f32 v39, v40, v41
	v_cvt_pk_bf16_f32 v40, v34, v35
	v_cvt_pk_bf16_f32 v41, v36, v37
	v_add_co_u32_e32 v250, vcc, 0x48000, v208
	s_nop 1
	v_addc_co_u32_e32 v251, vcc, 0, v209, vcc
	global_store_dwordx4 v[250:251], v[46:49], off
	global_store_dwordx4 v[250:251], v[38:41], off offset:256
	v_and_b32_e32 v212, 0xffff0000, v218
	v_lshlrev_b32_e32 v218, 16, v218
	v_fma_f32 v30, v30, v102, v218
	v_fma_f32 v31, v31, v103, v212
	v_and_b32_e32 v212, 0xffff0000, v219
	v_lshlrev_b32_e32 v219, 16, v219
	v_fma_f32 v32, v32, v104, v219
	v_fma_f32 v33, v33, v105, v212
	v_and_b32_e32 v212, 0xffff0000, v220
	v_lshlrev_b32_e32 v220, 16, v220
	v_fma_f32 v26, v26, v98, v220
	v_fma_f32 v27, v27, v99, v212
	v_and_b32_e32 v212, 0xffff0000, v221
	v_lshlrev_b32_e32 v221, 16, v221
	v_fma_f32 v28, v28, v100, v221
	v_fma_f32 v29, v29, v101, v212
	v_cvt_pk_bf16_f32 v30, v30, v31
	v_cvt_pk_bf16_f32 v31, v32, v33
	v_cvt_pk_bf16_f32 v32, v26, v27
	v_cvt_pk_bf16_f32 v33, v28, v29
	v_and_b32_e32 v212, 0xffff0000, v222
	v_lshlrev_b32_e32 v222, 16, v222
	v_fma_f32 v22, v22, v86, v222
	v_fma_f32 v23, v23, v87, v212
	v_and_b32_e32 v212, 0xffff0000, v223
	v_lshlrev_b32_e32 v223, 16, v223
	v_fma_f32 v24, v24, v88, v223
	v_fma_f32 v25, v25, v89, v212
	v_and_b32_e32 v212, 0xffff0000, v224
	v_lshlrev_b32_e32 v224, 16, v224
	v_fma_f32 v18, v18, v82, v224
	v_fma_f32 v19, v19, v83, v212
	v_and_b32_e32 v212, 0xffff0000, v225
	v_lshlrev_b32_e32 v225, 16, v225
	v_fma_f32 v20, v20, v84, v225
	v_fma_f32 v21, v21, v85, v212
	v_cvt_pk_bf16_f32 v22, v22, v23
	v_cvt_pk_bf16_f32 v23, v24, v25
	v_cvt_pk_bf16_f32 v24, v18, v19
	v_cvt_pk_bf16_f32 v25, v20, v21
	v_add_co_u32_e32 v250, vcc, 0x50000, v208
	s_nop 1
	v_addc_co_u32_e32 v251, vcc, 0, v209, vcc
	global_store_dwordx4 v[250:251], v[30:33], off
	global_store_dwordx4 v[250:251], v[22:25], off offset:256
	v_and_b32_e32 v212, 0xffff0000, v242
	v_lshlrev_b32_e32 v242, 16, v242
	v_fma_f32 v14, v14, v102, v242
	v_fma_f32 v15, v15, v103, v212
	v_and_b32_e32 v212, 0xffff0000, v243
	v_lshlrev_b32_e32 v243, 16, v243
	v_fma_f32 v16, v16, v104, v243
	v_fma_f32 v17, v17, v105, v212
	v_and_b32_e32 v212, 0xffff0000, v244
	v_lshlrev_b32_e32 v244, 16, v244
	v_fma_f32 v10, v10, v98, v244
	v_fma_f32 v11, v11, v99, v212
	v_and_b32_e32 v212, 0xffff0000, v245
	v_lshlrev_b32_e32 v245, 16, v245
	v_fma_f32 v12, v12, v100, v245
	v_fma_f32 v13, v13, v101, v212
	v_cvt_pk_bf16_f32 v14, v14, v15
	v_cvt_pk_bf16_f32 v15, v16, v17
	v_cvt_pk_bf16_f32 v16, v10, v11
	v_cvt_pk_bf16_f32 v17, v12, v13
	v_and_b32_e32 v212, 0xffff0000, v246
	v_lshlrev_b32_e32 v246, 16, v246
	v_fma_f32 v6, v6, v86, v246
	v_fma_f32 v7, v7, v87, v212
	v_and_b32_e32 v212, 0xffff0000, v247
	v_lshlrev_b32_e32 v247, 16, v247
	v_fma_f32 v8, v8, v88, v247
	v_fma_f32 v9, v9, v89, v212
	v_and_b32_e32 v212, 0xffff0000, v248
	v_lshlrev_b32_e32 v248, 16, v248
	v_fma_f32 v2, v2, v82, v248
	v_fma_f32 v3, v3, v83, v212
	v_and_b32_e32 v212, 0xffff0000, v249
	v_lshlrev_b32_e32 v249, 16, v249
	v_fma_f32 v4, v4, v84, v249
	v_fma_f32 v5, v5, v85, v212
	v_cvt_pk_bf16_f32 v6, v6, v7
	v_cvt_pk_bf16_f32 v7, v8, v9
	v_cvt_pk_bf16_f32 v8, v2, v3
	v_cvt_pk_bf16_f32 v9, v4, v5
	v_add_co_u32_e32 v250, vcc, 0x58000, v208
	s_nop 1
	v_addc_co_u32_e32 v251, vcc, 0, v209, vcc
	global_store_dwordx4 v[250:251], v[14:17], off
	global_store_dwordx4 v[250:251], v[6:9], off offset:256
	s_branch .Ldown_epi_done
.Ldown_epi_f32:
	v_and_b32_e32 v212, 0xffff0000, v152
	v_lshlrev_b32_e32 v152, 16, v152
	v_fma_f32 v142, v142, v102, v152
	v_fma_f32 v143, v143, v103, v212
	v_and_b32_e32 v212, 0xffff0000, v153
	v_lshlrev_b32_e32 v153, 16, v153
	v_fma_f32 v144, v144, v104, v153
	v_fma_f32 v145, v145, v105, v212
	v_and_b32_e32 v212, 0xffff0000, v154
	v_lshlrev_b32_e32 v154, 16, v154
	v_fma_f32 v138, v138, v98, v154
	v_fma_f32 v139, v139, v99, v212
	v_and_b32_e32 v212, 0xffff0000, v155
	v_lshlrev_b32_e32 v155, 16, v155
	v_fma_f32 v140, v140, v100, v155
	v_fma_f32 v141, v141, v101, v212
	v_and_b32_e32 v212, 0xffff0000, v156
	v_lshlrev_b32_e32 v156, 16, v156
	v_fma_f32 v134, v134, v86, v156
	v_fma_f32 v135, v135, v87, v212
	v_and_b32_e32 v212, 0xffff0000, v157
	v_lshlrev_b32_e32 v157, 16, v157
	v_fma_f32 v136, v136, v88, v157
	v_fma_f32 v137, v137, v89, v212
	v_and_b32_e32 v212, 0xffff0000, v158
	v_lshlrev_b32_e32 v158, 16, v158
	v_fma_f32 v130, v130, v82, v158
	v_fma_f32 v131, v131, v83, v212
	v_and_b32_e32 v212, 0xffff0000, v159
	v_lshlrev_b32_e32 v159, 16, v159
	v_fma_f32 v132, v132, v84, v159
	v_fma_f32 v133, v133, v85, v212
	global_store_dwordx4 v[210:211], v[142:145], off
	global_store_dwordx4 v[210:211], v[138:141], off offset:16
	global_store_dwordx4 v[210:211], v[134:137], off offset:512
	global_store_dwordx4 v[210:211], v[130:133], off offset:528
	v_and_b32_e32 v212, 0xffff0000, v160
	v_lshlrev_b32_e32 v160, 16, v160
	v_fma_f32 v126, v126, v102, v160
	v_fma_f32 v127, v127, v103, v212
	v_and_b32_e32 v212, 0xffff0000, v161
	v_lshlrev_b32_e32 v161, 16, v161
	v_fma_f32 v128, v128, v104, v161
	v_fma_f32 v129, v129, v105, v212
	v_and_b32_e32 v212, 0xffff0000, v162
; __device__ __forceinline__ unsigned cvt_pk_bf16(float lo, float hi) { f32x2_t v = {lo, hi}; bf16x2_t b = __builtin_convertvector(v, bf16x2_t); return __builtin_bit_cast(unsigned, b); }
; __device__ __forceinline__ float bflo(unsigned w) { return __uint_as_float(w << 16); }
; __device__ __forceinline__ float bfhi(unsigned w) { return __uint_as_float(w & 0xffff0000u); }
;     __device__ __forceinline__ void operator()(const f32x4 (&acc)[2][2][4][2], const Unit& u, int wr, int wc, int fr, int fq) const {
;     ...
;             for (int m = 0; m < 4; ++m) { const size_t off = (size_t)(row0 + ai * HALF + m * 16) * 1024 + col0;
; #pragma unroll
;                 for (int bj = 0; bj < 2; ++bj) {
;                     f32x4 x0, x1;
;                     if (xin_f32) { x0 = *(const f32x4*)(xin_f32 + off + bj * HALF); x1 = *(const f32x4*)(xin_f32 + off + bj * HALF + 4); }
;                     else { const u32x4 w = *(const u32x4*)(xin_b + off + bj * HALF); x0 = (f32x4){bflo(w.x), bfhi(w.x), bflo(w.y), bfhi(w.y)}; x1 = (f32x4){bflo(w.z), bfhi(w.z), bflo(w.w), bfhi(w.w)}; }
;                     x0 = x0 + gv[bj][0] * acc[ai][bj][m][0]; x1 = x1 + gv[bj][1] * acc[ai][bj][m][1];
;                     if (xout_f32) { *(f32x4*)(xout_f32 + off + bj * HALF) = x0; *(f32x4*)(xout_f32 + off + bj * HALF + 4) = x1; }
;                     else { u32x4 w; w.x = cvt_pk_bf16(x0[0], x0[1]); w.y = cvt_pk_bf16(x0[2], x0[3]); w.z = cvt_pk_bf16(x1[0], x1[1]); w.w = cvt_pk_bf16(x1[2], x1[3]); *(u32x4*)(xout_b + off + bj * HALF) = w; }
	v_lshlrev_b32_e32 v162, 16, v162
	v_fma_f32 v122, v122, v98, v162
	v_fma_f32 v123, v123, v99, v212
	v_and_b32_e32 v212, 0xffff0000, v163
	v_lshlrev_b32_e32 v163, 16, v163
	v_fma_f32 v124, v124, v100, v163
	v_fma_f32 v125, v125, v101, v212
	v_and_b32_e32 v212, 0xffff0000, v164
	v_lshlrev_b32_e32 v164, 16, v164
	v_fma_f32 v118, v118, v86, v164
	v_fma_f32 v119, v119, v87, v212
	v_and_b32_e32 v212, 0xffff0000, v165
	v_lshlrev_b32_e32 v165, 16, v165
	v_fma_f32 v120, v120, v88, v165
	v_fma_f32 v121, v121, v89, v212
	v_and_b32_e32 v212, 0xffff0000, v166
	v_lshlrev_b32_e32 v166, 16, v166
	v_fma_f32 v114, v114, v82, v166
	v_fma_f32 v115, v115, v83, v212
	v_and_b32_e32 v212, 0xffff0000, v167
	v_lshlrev_b32_e32 v167, 16, v167
	v_fma_f32 v116, v116, v84, v167
	v_fma_f32 v117, v117, v85, v212
	v_add_co_u32_e32 v250, vcc, 0x10000, v210
	s_nop 1
	v_addc_co_u32_e32 v251, vcc, 0, v211, vcc
	global_store_dwordx4 v[250:251], v[126:129], off
	global_store_dwordx4 v[250:251], v[122:125], off offset:16
	global_store_dwordx4 v[250:251], v[118:121], off offset:512
	global_store_dwordx4 v[250:251], v[114:117], off offset:528
	v_and_b32_e32 v212, 0xffff0000, v168
	v_lshlrev_b32_e32 v168, 16, v168
	v_fma_f32 v110, v110, v102, v168
	v_fma_f32 v111, v111, v103, v212
	v_and_b32_e32 v212, 0xffff0000, v169
	v_lshlrev_b32_e32 v169, 16, v169
	v_fma_f32 v112, v112, v104, v169
	v_fma_f32 v113, v113, v105, v212
	v_and_b32_e32 v212, 0xffff0000, v170
	v_lshlrev_b32_e32 v170, 16, v170
	v_fma_f32 v106, v106, v98, v170
	v_fma_f32 v107, v107, v99, v212
	v_and_b32_e32 v212, 0xffff0000, v171
	v_lshlrev_b32_e32 v171, 16, v171
	v_fma_f32 v108, v108, v100, v171
	v_fma_f32 v109, v109, v101, v212
	v_and_b32_e32 v212, 0xffff0000, v174
	v_lshlrev_b32_e32 v174, 16, v174
	v_fma_f32 v94, v94, v86, v174
	v_fma_f32 v95, v95, v87, v212
	v_and_b32_e32 v212, 0xffff0000, v175
	v_lshlrev_b32_e32 v175, 16, v175
	v_fma_f32 v96, v96, v88, v175
	v_fma_f32 v97, v97, v89, v212
	v_and_b32_e32 v212, 0xffff0000, v176
	v_lshlrev_b32_e32 v176, 16, v176
	v_fma_f32 v90, v90, v82, v176
	v_fma_f32 v91, v91, v83, v212
	v_and_b32_e32 v212, 0xffff0000, v177
	v_lshlrev_b32_e32 v177, 16, v177
	v_fma_f32 v92, v92, v84, v177
	v_fma_f32 v93, v93, v85, v212
	v_add_co_u32_e32 v250, vcc, 0x20000, v210
	s_nop 1
	v_addc_co_u32_e32 v251, vcc, 0, v211, vcc
	global_store_dwordx4 v[250:251], v[110:113], off
	global_store_dwordx4 v[250:251], v[106:109], off offset:16
	global_store_dwordx4 v[250:251], v[94:97], off offset:512
	global_store_dwordx4 v[250:251], v[90:93], off offset:528
	v_and_b32_e32 v212, 0xffff0000, v178
	v_lshlrev_b32_e32 v178, 16, v178
	v_fma_f32 v78, v78, v102, v178
	v_fma_f32 v79, v79, v103, v212
	v_and_b32_e32 v212, 0xffff0000, v179
	v_lshlrev_b32_e32 v179, 16, v179
	v_fma_f32 v80, v80, v104, v179
	v_fma_f32 v81, v81, v105, v212
	v_and_b32_e32 v212, 0xffff0000, v180
	v_lshlrev_b32_e32 v180, 16, v180
	v_fma_f32 v74, v74, v98, v180
	v_fma_f32 v75, v75, v99, v212
	v_and_b32_e32 v212, 0xffff0000, v181
	v_lshlrev_b32_e32 v181, 16, v181
	v_fma_f32 v76, v76, v100, v181
	v_fma_f32 v77, v77, v101, v212
	v_and_b32_e32 v212, 0xffff0000, v182
	v_lshlrev_b32_e32 v182, 16, v182
	v_fma_f32 v70, v70, v86, v182
	v_fma_f32 v71, v71, v87, v212
	v_and_b32_e32 v212, 0xffff0000, v183
	v_lshlrev_b32_e32 v183, 16, v183
	v_fma_f32 v72, v72, v88, v183
	v_fma_f32 v73, v73, v89, v212
	v_and_b32_e32 v212, 0xffff0000, v184
	v_lshlrev_b32_e32 v184, 16, v184
	v_fma_f32 v66, v66, v82, v184
	v_fma_f32 v67, v67, v83, v212
	v_and_b32_e32 v212, 0xffff0000, v185
	v_lshlrev_b32_e32 v185, 16, v185
	v_fma_f32 v68, v68, v84, v185
	v_fma_f32 v69, v69, v85, v212
	v_add_co_u32_e32 v250, vcc, 0x30000, v210
	s_nop 1
	v_addc_co_u32_e32 v251, vcc, 0, v211, vcc
	global_store_dwordx4 v[250:251], v[78:81], off
	global_store_dwordx4 v[250:251], v[74:77], off offset:16
	global_store_dwordx4 v[250:251], v[70:73], off offset:512
	global_store_dwordx4 v[250:251], v[66:69], off offset:528
	v_and_b32_e32 v212, 0xffff0000, v186
	v_lshlrev_b32_e32 v186, 16, v186
	v_fma_f32 v62, v62, v102, v186
	v_fma_f32 v63, v63, v103, v212
	v_and_b32_e32 v212, 0xffff0000, v187
	v_lshlrev_b32_e32 v187, 16, v187
	v_fma_f32 v64, v64, v104, v187
	v_fma_f32 v65, v65, v105, v212
	v_and_b32_e32 v212, 0xffff0000, v188
	v_lshlrev_b32_e32 v188, 16, v188
	v_fma_f32 v58, v58, v98, v188
	v_fma_f32 v59, v59, v99, v212
	v_and_b32_e32 v212, 0xffff0000, v189
	v_lshlrev_b32_e32 v189, 16, v189
	v_fma_f32 v60, v60, v100, v189
	v_fma_f32 v61, v61, v101, v212
	v_and_b32_e32 v212, 0xffff0000, v190
	v_lshlrev_b32_e32 v190, 16, v190
	v_fma_f32 v54, v54, v86, v190
	v_fma_f32 v55, v55, v87, v212
	v_and_b32_e32 v212, 0xffff0000, v191
	v_lshlrev_b32_e32 v191, 16, v191
	v_fma_f32 v56, v56, v88, v191
	v_fma_f32 v57, v57, v89, v212
; __device__ __forceinline__ unsigned cvt_pk_bf16(float lo, float hi) { f32x2_t v = {lo, hi}; bf16x2_t b = __builtin_convertvector(v, bf16x2_t); return __builtin_bit_cast(unsigned, b); }
; __device__ __forceinline__ float bflo(unsigned w) { return __uint_as_float(w << 16); }
; __device__ __forceinline__ float bfhi(unsigned w) { return __uint_as_float(w & 0xffff0000u); }
;     __device__ __forceinline__ void operator()(const f32x4 (&acc)[2][2][4][2], const Unit& u, int wr, int wc, int fr, int fq) const {
;     ...
;             for (int m = 0; m < 4; ++m) { const size_t off = (size_t)(row0 + ai * HALF + m * 16) * 1024 + col0;
; #pragma unroll
;                 for (int bj = 0; bj < 2; ++bj) {
;                     f32x4 x0, x1;
;                     if (xin_f32) { x0 = *(const f32x4*)(xin_f32 + off + bj * HALF); x1 = *(const f32x4*)(xin_f32 + off + bj * HALF + 4); }
;                     else { const u32x4 w = *(const u32x4*)(xin_b + off + bj * HALF); x0 = (f32x4){bflo(w.x), bfhi(w.x), bflo(w.y), bfhi(w.y)}; x1 = (f32x4){bflo(w.z), bfhi(w.z), bflo(w.w), bfhi(w.w)}; }
;                     x0 = x0 + gv[bj][0] * acc[ai][bj][m][0]; x1 = x1 + gv[bj][1] * acc[ai][bj][m][1];
;                     if (xout_f32) { *(f32x4*)(xout_f32 + off + bj * HALF) = x0; *(f32x4*)(xout_f32 + off + bj * HALF + 4) = x1; }
;                     else { u32x4 w; w.x = cvt_pk_bf16(x0[0], x0[1]); w.y = cvt_pk_bf16(x0[2], x0[3]); w.z = cvt_pk_bf16(x1[0], x1[1]); w.w = cvt_pk_bf16(x1[2], x1[3]); *(u32x4*)(xout_b + off + bj * HALF) = w; }
	v_and_b32_e32 v212, 0xffff0000, v192
	v_lshlrev_b32_e32 v192, 16, v192
	v_fma_f32 v50, v50, v82, v192
	v_fma_f32 v51, v51, v83, v212
	v_and_b32_e32 v212, 0xffff0000, v193
	v_lshlrev_b32_e32 v193, 16, v193
	v_fma_f32 v52, v52, v84, v193
	v_fma_f32 v53, v53, v85, v212
	v_add_co_u32_e32 v250, vcc, 0x80000, v210
	s_nop 1
	v_addc_co_u32_e32 v251, vcc, 0, v211, vcc
	global_store_dwordx4 v[250:251], v[62:65], off
	global_store_dwordx4 v[250:251], v[58:61], off offset:16
	global_store_dwordx4 v[250:251], v[54:57], off offset:512
	global_store_dwordx4 v[250:251], v[50:53], off offset:528
	v_and_b32_e32 v212, 0xffff0000, v194
	v_lshlrev_b32_e32 v194, 16, v194
	v_fma_f32 v46, v46, v102, v194
	v_fma_f32 v47, v47, v103, v212
	v_and_b32_e32 v212, 0xffff0000, v195
	v_lshlrev_b32_e32 v195, 16, v195
	v_fma_f32 v48, v48, v104, v195
	v_fma_f32 v49, v49, v105, v212
	v_and_b32_e32 v212, 0xffff0000, v196
	v_lshlrev_b32_e32 v196, 16, v196
	v_fma_f32 v42, v42, v98, v196
	v_fma_f32 v43, v43, v99, v212
	v_and_b32_e32 v212, 0xffff0000, v197
	v_lshlrev_b32_e32 v197, 16, v197
	v_fma_f32 v44, v44, v100, v197
	v_fma_f32 v45, v45, v101, v212
	v_and_b32_e32 v212, 0xffff0000, v198
	v_lshlrev_b32_e32 v198, 16, v198
	v_fma_f32 v38, v38, v86, v198
	v_fma_f32 v39, v39, v87, v212
	v_and_b32_e32 v212, 0xffff0000, v199
	v_lshlrev_b32_e32 v199, 16, v199
	v_fma_f32 v40, v40, v88, v199
	v_fma_f32 v41, v41, v89, v212
	v_and_b32_e32 v212, 0xffff0000, v200
	v_lshlrev_b32_e32 v200, 16, v200
	v_fma_f32 v34, v34, v82, v200
	v_fma_f32 v35, v35, v83, v212
	v_and_b32_e32 v212, 0xffff0000, v201
	v_lshlrev_b32_e32 v201, 16, v201
	v_fma_f32 v36, v36, v84, v201
	v_fma_f32 v37, v37, v85, v212
	v_add_co_u32_e32 v250, vcc, 0x90000, v210
	s_nop 1
	v_addc_co_u32_e32 v251, vcc, 0, v211, vcc
	global_store_dwordx4 v[250:251], v[46:49], off
	global_store_dwordx4 v[250:251], v[42:45], off offset:16
	global_store_dwordx4 v[250:251], v[38:41], off offset:512
	global_store_dwordx4 v[250:251], v[34:37], off offset:528
	v_and_b32_e32 v212, 0xffff0000, v218
	v_lshlrev_b32_e32 v218, 16, v218
	v_fma_f32 v30, v30, v102, v218
	v_fma_f32 v31, v31, v103, v212
	v_and_b32_e32 v212, 0xffff0000, v219
	v_lshlrev_b32_e32 v219, 16, v219
	v_fma_f32 v32, v32, v104, v219
	v_fma_f32 v33, v33, v105, v212
	v_and_b32_e32 v212, 0xffff0000, v220
	v_lshlrev_b32_e32 v220, 16, v220
	v_fma_f32 v26, v26, v98, v220
	v_fma_f32 v27, v27, v99, v212
	v_and_b32_e32 v212, 0xffff0000, v221
	v_lshlrev_b32_e32 v221, 16, v221
	v_fma_f32 v28, v28, v100, v221
	v_fma_f32 v29, v29, v101, v212
	v_and_b32_e32 v212, 0xffff0000, v222
	v_lshlrev_b32_e32 v222, 16, v222
	v_fma_f32 v22, v22, v86, v222
	v_fma_f32 v23, v23, v87, v212
	v_and_b32_e32 v212, 0xffff0000, v223
	v_lshlrev_b32_e32 v223, 16, v223
	v_fma_f32 v24, v24, v88, v223
	v_fma_f32 v25, v25, v89, v212
	v_and_b32_e32 v212, 0xffff0000, v224
	v_lshlrev_b32_e32 v224, 16, v224
	v_fma_f32 v18, v18, v82, v224
	v_fma_f32 v19, v19, v83, v212
	v_and_b32_e32 v212, 0xffff0000, v225
	v_lshlrev_b32_e32 v225, 16, v225
	v_fma_f32 v20, v20, v84, v225
	v_fma_f32 v21, v21, v85, v212
	v_add_co_u32_e32 v250, vcc, 0xa0000, v210
	s_nop 1
	v_addc_co_u32_e32 v251, vcc, 0, v211, vcc
	global_store_dwordx4 v[250:251], v[30:33], off
	global_store_dwordx4 v[250:251], v[26:29], off offset:16
	global_store_dwordx4 v[250:251], v[22:25], off offset:512
	global_store_dwordx4 v[250:251], v[18:21], off offset:528
	v_and_b32_e32 v212, 0xffff0000, v242
	v_lshlrev_b32_e32 v242, 16, v242
	v_fma_f32 v14, v14, v102, v242
	v_fma_f32 v15, v15, v103, v212
	v_and_b32_e32 v212, 0xffff0000, v243
	v_lshlrev_b32_e32 v243, 16, v243
	v_fma_f32 v16, v16, v104, v243
	v_fma_f32 v17, v17, v105, v212
	v_and_b32_e32 v212, 0xffff0000, v244
	v_lshlrev_b32_e32 v244, 16, v244
	v_fma_f32 v10, v10, v98, v244
	v_fma_f32 v11, v11, v99, v212
	v_and_b32_e32 v212, 0xffff0000, v245
	v_lshlrev_b32_e32 v245, 16, v245
	v_fma_f32 v12, v12, v100, v245
	v_fma_f32 v13, v13, v101, v212
	v_and_b32_e32 v212, 0xffff0000, v246
	v_lshlrev_b32_e32 v246, 16, v246
	v_fma_f32 v6, v6, v86, v246
	v_fma_f32 v7, v7, v87, v212
	v_and_b32_e32 v212, 0xffff0000, v247
	v_lshlrev_b32_e32 v247, 16, v247
	v_fma_f32 v8, v8, v88, v247
	v_fma_f32 v9, v9, v89, v212
	v_and_b32_e32 v212, 0xffff0000, v248
	v_lshlrev_b32_e32 v248, 16, v248
	v_fma_f32 v2, v2, v82, v248
	v_fma_f32 v3, v3, v83, v212
	v_and_b32_e32 v212, 0xffff0000, v249
	v_lshlrev_b32_e32 v249, 16, v249
	v_fma_f32 v4, v4, v84, v249
	v_fma_f32 v5, v5, v85, v212
	v_add_co_u32_e32 v250, vcc, 0xb0000, v210
	s_nop 1
	v_addc_co_u32_e32 v251, vcc, 0, v211, vcc
	global_store_dwordx4 v[250:251], v[14:17], off
	global_store_dwordx4 v[250:251], v[10:13], off offset:16
	global_store_dwordx4 v[250:251], v[6:9], off offset:512
	global_store_dwordx4 v[250:251], v[2:5], off offset:528
